# adds: 64-byte alignment (s_nop fill) of the GEMM K-loop heads and the MLA tile loop head
# baseline (speedup 1.0000x reference)
.Lzgo_1:
	s_add_u32 s22, s22, 0x80
	s_addc_u32 s23, s23, 0
	s_add_u32 vcc_lo, s66, 0x100
	s_addc_u32 vcc_hi, s67, 0
	s_mov_b32 s66, 0
	s_add_i32 s88, s66, 2
	s_add_u32 s62, s22, 0x80
	s_addc_u32 s63, s23, 0
	s_add_i32 s89, 0, 0x10000
	s_cmp_eq_u32 s93, s66
	s_cselect_b32 s67, s3, s63
	s_cselect_b32 s66, s2, s62
	v_add_u32_e32 v149, s89, v146
	s_cselect_b32 s63, s21, vcc_hi
	s_cselect_b32 s62, s20, vcc_lo
	s_add_i32 s31, 0, 0x14000
	ds_read_b128 v[142:145], v149
	ds_read_b128 v[150:153], v149 offset:1024
	ds_read_b128 v[154:157], v149 offset:2048
	ds_read_b128 v[158:161], v149 offset:3072
	v_add_u32_e32 v149, s31, v146
	ds_read_b128 v[162:165], v149
	ds_read_b128 v[166:169], v149 offset:1024
	ds_read_b128 v[170:173], v149 offset:2048
	ds_read_b128 v[174:177], v149 offset:3072
	v_lshl_add_u64 v[218:219], s[22:23], 0, v[138:139]
	s_add_i32 m0, s77, 0xc000
	ds_read_b128 v[178:181], v148
	ds_read_b128 v[182:185], v148 offset:1024
	ds_read_b128 v[186:189], v148 offset:2048
	ds_read_b128 v[190:193], v148 offset:3072
	ds_read_b128 v[194:197], v148 offset:4096
	ds_read_b128 v[198:201], v148 offset:5120
	ds_read_b128 v[202:205], v148 offset:6144
	ds_read_b128 v[214:217], v148 offset:7168
	global_load_lds_dwordx4 v[218:219], off
	v_lshl_add_u64 v[218:219], s[22:23], 0, v[140:141]
	s_add_i32 m0, s77, 0xe000
	s_nop 0
	global_load_lds_dwordx4 v[218:219], off
	s_waitcnt vmcnt(8)
	s_waitcnt lgkmcnt(0)
	s_barrier
	s_setprio 1
	s_waitcnt lgkmcnt(0)
	v_mfma_f32_16x16x32_bf16 v[122:125], v[142:145], v[178:181], 0
	v_mfma_f32_16x16x32_bf16 v[118:121], v[154:157], v[178:181], 0
	v_mfma_f32_16x16x32_bf16 v[110:113], v[142:145], v[186:189], 0
	v_mfma_f32_16x16x32_bf16 v[102:105], v[154:157], v[186:189], 0
	v_mfma_f32_16x16x32_bf16 v[94:97], v[142:145], v[194:197], 0
	v_mfma_f32_16x16x32_bf16 v[86:89], v[154:157], v[194:197], 0
	v_mfma_f32_16x16x32_bf16 v[78:81], v[142:145], v[202:205], 0
	v_mfma_f32_16x16x32_bf16 v[70:73], v[154:157], v[202:205], 0
	v_mfma_f32_16x16x32_bf16 v[122:125], v[150:153], v[182:185], v[122:125]
	v_mfma_f32_16x16x32_bf16 v[118:121], v[158:161], v[182:185], v[118:121]
	v_mfma_f32_16x16x32_bf16 v[110:113], v[150:153], v[190:193], v[110:113]
	v_mfma_f32_16x16x32_bf16 v[102:105], v[158:161], v[190:193], v[102:105]
	v_mfma_f32_16x16x32_bf16 v[94:97], v[150:153], v[198:201], v[94:97]
	v_mfma_f32_16x16x32_bf16 v[86:89], v[158:161], v[198:201], v[86:89]
	v_mfma_f32_16x16x32_bf16 v[78:81], v[150:153], v[214:217], v[78:81]
	v_mfma_f32_16x16x32_bf16 v[70:73], v[158:161], v[214:217], v[70:73]
	s_setprio 0
	s_setprio 1
	v_mfma_f32_16x16x32_bf16 v[126:129], v[162:165], v[178:181], 0
	v_mfma_f32_16x16x32_bf16 v[114:117], v[170:173], v[178:181], 0
	v_mfma_f32_16x16x32_bf16 v[106:109], v[162:165], v[186:189], 0
	v_mfma_f32_16x16x32_bf16 v[98:101], v[170:173], v[186:189], 0
	v_mfma_f32_16x16x32_bf16 v[90:93], v[162:165], v[194:197], 0
	v_mfma_f32_16x16x32_bf16 v[82:85], v[170:173], v[194:197], 0
	v_mfma_f32_16x16x32_bf16 v[74:77], v[162:165], v[202:205], 0
	v_mfma_f32_16x16x32_bf16 v[66:69], v[170:173], v[202:205], 0
	v_mfma_f32_16x16x32_bf16 v[126:129], v[166:169], v[182:185], v[126:129]
	v_mfma_f32_16x16x32_bf16 v[114:117], v[174:177], v[182:185], v[114:117]
	v_mfma_f32_16x16x32_bf16 v[106:109], v[166:169], v[190:193], v[106:109]
	v_mfma_f32_16x16x32_bf16 v[98:101], v[174:177], v[190:193], v[98:101]
	v_mfma_f32_16x16x32_bf16 v[90:93], v[166:169], v[198:201], v[90:93]
	v_mfma_f32_16x16x32_bf16 v[82:85], v[174:177], v[198:201], v[82:85]
	v_mfma_f32_16x16x32_bf16 v[74:77], v[166:169], v[214:217], v[74:77]
	v_mfma_f32_16x16x32_bf16 v[66:69], v[174:177], v[214:217], v[66:69]
	s_setprio 0
	s_barrier
	s_add_i32 s89, s89, s74
	v_lshl_add_u64 v[218:219], s[62:63], 0, v[134:135]
	s_mov_b32 m0, s89
	ds_read_b128 v[178:181], v148 offset:16384
	ds_read_b128 v[182:185], v148 offset:17408
	ds_read_b128 v[186:189], v148 offset:18432
	ds_read_b128 v[190:193], v148 offset:19456
	ds_read_b128 v[194:197], v148 offset:20480
	ds_read_b128 v[198:201], v148 offset:21504
	ds_read_b128 v[202:205], v148 offset:22528
	ds_read_b128 v[214:217], v148 offset:23552
	global_load_lds_dwordx4 v[218:219], off
	s_add_i32 m0, s89, 0x2000
	v_lshl_add_u64 v[220:221], s[62:63], 0, v[130:131]
	s_add_u32 s62, s62, s8
	s_addc_u32 s63, s63, s9
	s_add_i32 s31, s31, s74
	global_load_lds_dwordx4 v[220:221], off
	v_lshl_add_u64 v[222:223], s[62:63], 0, v[134:135]
	s_mov_b32 m0, s31
	v_lshl_add_u64 v[224:225], s[62:63], 0, v[130:131]
	global_load_lds_dwordx4 v[222:223], off
	s_add_i32 m0, s31, 0x2000
	v_lshl_add_u64 v[226:227], s[66:67], 0, v[136:137]
	global_load_lds_dwordx4 v[224:225], off
	s_mov_b32 m0, s77
	v_lshl_add_u64 v[236:237], s[66:67], 0, v[132:133]
	global_load_lds_dwordx4 v[226:227], off
	s_mov_b32 m0, s78
	s_nop 0
	global_load_lds_dwordx4 v[236:237], off
	s_waitcnt vmcnt(8)
	s_waitcnt lgkmcnt(0)
	s_barrier
	s_setprio 1
	s_waitcnt lgkmcnt(0)
	v_mfma_f32_16x16x32_bf16 v[62:65], v[142:145], v[178:181], 0
	v_mfma_f32_16x16x32_bf16 v[54:57], v[154:157], v[178:181], 0
	v_mfma_f32_16x16x32_bf16 v[46:49], v[142:145], v[186:189], 0
	v_mfma_f32_16x16x32_bf16 v[38:41], v[154:157], v[186:189], 0
	v_mfma_f32_16x16x32_bf16 v[30:33], v[142:145], v[194:197], 0
	v_mfma_f32_16x16x32_bf16 v[22:25], v[154:157], v[194:197], 0
	v_mfma_f32_16x16x32_bf16 v[14:17], v[142:145], v[202:205], 0
	v_mfma_f32_16x16x32_bf16 v[6:9], v[154:157], v[202:205], 0
	v_mfma_f32_16x16x32_bf16 v[62:65], v[150:153], v[182:185], v[62:65]
	v_mfma_f32_16x16x32_bf16 v[54:57], v[158:161], v[182:185], v[54:57]
	v_mfma_f32_16x16x32_bf16 v[46:49], v[150:153], v[190:193], v[46:49]
	v_mfma_f32_16x16x32_bf16 v[38:41], v[158:161], v[190:193], v[38:41]
	v_mfma_f32_16x16x32_bf16 v[30:33], v[150:153], v[198:201], v[30:33]
	v_mfma_f32_16x16x32_bf16 v[22:25], v[158:161], v[198:201], v[22:25]
	v_mfma_f32_16x16x32_bf16 v[14:17], v[150:153], v[214:217], v[14:17]
	v_mfma_f32_16x16x32_bf16 v[6:9], v[158:161], v[214:217], v[6:9]
	s_setprio 0
	s_setprio 1
	v_mfma_f32_16x16x32_bf16 v[58:61], v[162:165], v[178:181], 0
	v_mfma_f32_16x16x32_bf16 v[50:53], v[170:173], v[178:181], 0
	v_mfma_f32_16x16x32_bf16 v[42:45], v[162:165], v[186:189], 0
	v_mfma_f32_16x16x32_bf16 v[34:37], v[170:173], v[186:189], 0
	v_mfma_f32_16x16x32_bf16 v[26:29], v[162:165], v[194:197], 0
	v_mfma_f32_16x16x32_bf16 v[18:21], v[170:173], v[194:197], 0
	v_mfma_f32_16x16x32_bf16 v[10:13], v[162:165], v[202:205], 0
	v_mfma_f32_16x16x32_bf16 v[2:5], v[170:173], v[202:205], 0
	v_mfma_f32_16x16x32_bf16 v[58:61], v[166:169], v[182:185], v[58:61]
	v_mfma_f32_16x16x32_bf16 v[50:53], v[174:177], v[182:185], v[50:53]
	v_mfma_f32_16x16x32_bf16 v[42:45], v[166:169], v[190:193], v[42:45]
	v_mfma_f32_16x16x32_bf16 v[34:37], v[174:177], v[190:193], v[34:37]
	v_mfma_f32_16x16x32_bf16 v[26:29], v[166:169], v[198:201], v[26:29]
	v_mfma_f32_16x16x32_bf16 v[18:21], v[174:177], v[198:201], v[18:21]
	v_mfma_f32_16x16x32_bf16 v[10:13], v[166:169], v[214:217], v[10:13]
	v_mfma_f32_16x16x32_bf16 v[2:5], v[174:177], v[214:217], v[2:5]
	s_setprio 0
	s_barrier
	s_add_i32 s31, 0, 0x18000
	v_add_u32_e32 v149, s31, v146
	s_add_i32 s89, 0, 0x1c000
	ds_read_b128 v[142:145], v149
	ds_read_b128 v[150:153], v149 offset:1024
	ds_read_b128 v[154:157], v149 offset:2048
	ds_read_b128 v[158:161], v149 offset:3072
	v_add_u32_e32 v149, s89, v146
	ds_read_b128 v[162:165], v149
	ds_read_b128 v[166:169], v149 offset:1024
	ds_read_b128 v[170:173], v149 offset:2048
	ds_read_b128 v[174:177], v149 offset:3072
	s_add_u32 s62, s66, s8
	s_addc_u32 s63, s67, s9
	s_mov_b32 m0, s79
	v_lshl_add_u64 v[238:239], s[62:63], 0, v[136:137]
	ds_read_b128 v[178:181], v148 offset:32768
	ds_read_b128 v[182:185], v148 offset:33792
	ds_read_b128 v[186:189], v148 offset:34816
	ds_read_b128 v[190:193], v148 offset:35840
	ds_read_b128 v[194:197], v148 offset:36864
	ds_read_b128 v[198:201], v148 offset:37888
	ds_read_b128 v[202:205], v148 offset:38912
	ds_read_b128 v[214:217], v148 offset:39936
	global_load_lds_dwordx4 v[238:239], off
	v_lshl_add_u64 v[238:239], s[62:63], 0, v[132:133]
	s_mov_b32 m0, s90
	s_nop 0
	global_load_lds_dwordx4 v[238:239], off
	s_waitcnt vmcnt(8)
	s_waitcnt lgkmcnt(0)
	s_barrier
	s_setprio 1
	s_waitcnt lgkmcnt(0)
	v_mfma_f32_16x16x32_bf16 v[122:125], v[142:145], v[178:181], v[122:125]
	v_mfma_f32_16x16x32_bf16 v[118:121], v[154:157], v[178:181], v[118:121]
	v_mfma_f32_16x16x32_bf16 v[110:113], v[142:145], v[186:189], v[110:113]
	v_mfma_f32_16x16x32_bf16 v[102:105], v[154:157], v[186:189], v[102:105]
	v_mfma_f32_16x16x32_bf16 v[94:97], v[142:145], v[194:197], v[94:97]
	v_mfma_f32_16x16x32_bf16 v[86:89], v[154:157], v[194:197], v[86:89]
	v_mfma_f32_16x16x32_bf16 v[78:81], v[142:145], v[202:205], v[78:81]
	v_mfma_f32_16x16x32_bf16 v[70:73], v[154:157], v[202:205], v[70:73]
	v_mfma_f32_16x16x32_bf16 v[122:125], v[150:153], v[182:185], v[122:125]
	v_mfma_f32_16x16x32_bf16 v[118:121], v[158:161], v[182:185], v[118:121]
	v_mfma_f32_16x16x32_bf16 v[110:113], v[150:153], v[190:193], v[110:113]
	v_mfma_f32_16x16x32_bf16 v[102:105], v[158:161], v[190:193], v[102:105]
	v_mfma_f32_16x16x32_bf16 v[94:97], v[150:153], v[198:201], v[94:97]
	v_mfma_f32_16x16x32_bf16 v[86:89], v[158:161], v[198:201], v[86:89]
	v_mfma_f32_16x16x32_bf16 v[78:81], v[150:153], v[214:217], v[78:81]
	v_mfma_f32_16x16x32_bf16 v[70:73], v[158:161], v[214:217], v[70:73]
	s_setprio 0
	s_setprio 1
	v_mfma_f32_16x16x32_bf16 v[126:129], v[162:165], v[178:181], v[126:129]
	v_mfma_f32_16x16x32_bf16 v[114:117], v[170:173], v[178:181], v[114:117]
	v_mfma_f32_16x16x32_bf16 v[106:109], v[162:165], v[186:189], v[106:109]
	v_mfma_f32_16x16x32_bf16 v[98:101], v[170:173], v[186:189], v[98:101]
	v_mfma_f32_16x16x32_bf16 v[90:93], v[162:165], v[194:197], v[90:93]
	v_mfma_f32_16x16x32_bf16 v[82:85], v[170:173], v[194:197], v[82:85]
	v_mfma_f32_16x16x32_bf16 v[74:77], v[162:165], v[202:205], v[74:77]
	v_mfma_f32_16x16x32_bf16 v[66:69], v[170:173], v[202:205], v[66:69]
	v_mfma_f32_16x16x32_bf16 v[126:129], v[166:169], v[182:185], v[126:129]
	v_mfma_f32_16x16x32_bf16 v[114:117], v[174:177], v[182:185], v[114:117]
	v_mfma_f32_16x16x32_bf16 v[106:109], v[166:169], v[190:193], v[106:109]
	v_mfma_f32_16x16x32_bf16 v[98:101], v[174:177], v[190:193], v[98:101]
	v_mfma_f32_16x16x32_bf16 v[90:93], v[166:169], v[198:201], v[90:93]
	v_mfma_f32_16x16x32_bf16 v[82:85], v[174:177], v[198:201], v[82:85]
	v_mfma_f32_16x16x32_bf16 v[74:77], v[166:169], v[214:217], v[74:77]
	v_mfma_f32_16x16x32_bf16 v[66:69], v[174:177], v[214:217], v[66:69]
	s_setprio 0
	s_barrier
	s_add_i32 s31, s31, s74
	v_lshl_add_u64 v[218:219], v[218:219], 0, s[60:61]
	s_mov_b32 m0, s31
	ds_read_b128 v[178:181], v148 offset:49152
	ds_read_b128 v[182:185], v148 offset:50176
	ds_read_b128 v[186:189], v148 offset:51200
	ds_read_b128 v[190:193], v148 offset:52224
	ds_read_b128 v[194:197], v148 offset:53248
	ds_read_b128 v[198:201], v148 offset:54272
	ds_read_b128 v[202:205], v148 offset:55296
	ds_read_b128 v[214:217], v148 offset:56320
	global_load_lds_dwordx4 v[218:219], off
	v_lshl_add_u64 v[218:219], v[220:221], 0, s[60:61]
	s_add_i32 m0, s31, 0x2000
	s_add_i32 s31, s89, s74
	global_load_lds_dwordx4 v[218:219], off
	v_lshl_add_u64 v[218:219], v[222:223], 0, s[60:61]
	s_mov_b32 m0, s31
	s_nop 0
	global_load_lds_dwordx4 v[218:219], off
	v_lshl_add_u64 v[218:219], v[224:225], 0, s[60:61]
	s_add_i32 m0, s31, 0x2000
	s_nop 0
	global_load_lds_dwordx4 v[218:219], off
	v_lshl_add_u64 v[218:219], v[226:227], 0, s[60:61]
	s_mov_b32 m0, s91
	s_nop 0
	global_load_lds_dwordx4 v[218:219], off
	v_lshl_add_u64 v[218:219], v[236:237], 0, s[60:61]
	s_mov_b32 m0, s92
	s_nop 0
	global_load_lds_dwordx4 v[218:219], off
	s_waitcnt vmcnt(8)
	s_waitcnt lgkmcnt(0)
	s_barrier
	s_setprio 1
	s_waitcnt lgkmcnt(0)
	v_mfma_f32_16x16x32_bf16 v[62:65], v[142:145], v[178:181], v[62:65]
	v_mfma_f32_16x16x32_bf16 v[54:57], v[154:157], v[178:181], v[54:57]
	v_mfma_f32_16x16x32_bf16 v[46:49], v[142:145], v[186:189], v[46:49]
	v_mfma_f32_16x16x32_bf16 v[38:41], v[154:157], v[186:189], v[38:41]
	v_mfma_f32_16x16x32_bf16 v[30:33], v[142:145], v[194:197], v[30:33]
	v_mfma_f32_16x16x32_bf16 v[22:25], v[154:157], v[194:197], v[22:25]
	v_mfma_f32_16x16x32_bf16 v[14:17], v[142:145], v[202:205], v[14:17]
	v_mfma_f32_16x16x32_bf16 v[6:9], v[154:157], v[202:205], v[6:9]
	v_mfma_f32_16x16x32_bf16 v[62:65], v[150:153], v[182:185], v[62:65]
	v_mfma_f32_16x16x32_bf16 v[54:57], v[158:161], v[182:185], v[54:57]
	v_mfma_f32_16x16x32_bf16 v[46:49], v[150:153], v[190:193], v[46:49]
	v_mfma_f32_16x16x32_bf16 v[38:41], v[158:161], v[190:193], v[38:41]
	v_mfma_f32_16x16x32_bf16 v[30:33], v[150:153], v[198:201], v[30:33]
	v_mfma_f32_16x16x32_bf16 v[22:25], v[158:161], v[198:201], v[22:25]
	v_mfma_f32_16x16x32_bf16 v[14:17], v[150:153], v[214:217], v[14:17]
	v_mfma_f32_16x16x32_bf16 v[6:9], v[158:161], v[214:217], v[6:9]
	s_setprio 0
	s_setprio 1
	v_mfma_f32_16x16x32_bf16 v[58:61], v[162:165], v[178:181], v[58:61]
	v_mfma_f32_16x16x32_bf16 v[50:53], v[170:173], v[178:181], v[50:53]
	v_mfma_f32_16x16x32_bf16 v[42:45], v[162:165], v[186:189], v[42:45]
	v_mfma_f32_16x16x32_bf16 v[34:37], v[170:173], v[186:189], v[34:37]
	v_mfma_f32_16x16x32_bf16 v[26:29], v[162:165], v[194:197], v[26:29]
	v_mfma_f32_16x16x32_bf16 v[18:21], v[170:173], v[194:197], v[18:21]
	v_mfma_f32_16x16x32_bf16 v[10:13], v[162:165], v[202:205], v[10:13]
	v_mfma_f32_16x16x32_bf16 v[2:5], v[170:173], v[202:205], v[2:5]
	v_mfma_f32_16x16x32_bf16 v[58:61], v[166:169], v[182:185], v[58:61]
	v_mfma_f32_16x16x32_bf16 v[50:53], v[174:177], v[182:185], v[50:53]
	v_mfma_f32_16x16x32_bf16 v[42:45], v[166:169], v[190:193], v[42:45]
	v_mfma_f32_16x16x32_bf16 v[34:37], v[174:177], v[190:193], v[34:37]
	v_mfma_f32_16x16x32_bf16 v[26:29], v[166:169], v[198:201], v[26:29]
	v_mfma_f32_16x16x32_bf16 v[18:21], v[174:177], v[198:201], v[18:21]
	v_mfma_f32_16x16x32_bf16 v[10:13], v[166:169], v[214:217], v[10:13]
	v_mfma_f32_16x16x32_bf16 v[2:5], v[174:177], v[214:217], v[2:5]
	s_setprio 0
	s_barrier
	s_add_u32 s22, s22, 0x100
	s_addc_u32 s23, s23, 0
	s_add_u32 vcc_lo, vcc_lo, 0x100
	s_addc_u32 vcc_hi, vcc_hi, 0
	s_cmp_ge_i32 s88, s52
	s_mov_b32 s66, s88
	s_cbranch_scc1 .LBB0_288
	.p2alignl 6, 3212836864

.Lzgo_2:
	s_add_u32 s20, s20, 0x80
	s_addc_u32 s21, s21, 0
	s_add_u32 vcc_lo, s22, 0x100
	s_addc_u32 vcc_hi, s23, 0
	s_mov_b32 s22, 0
	s_add_i32 s88, s22, 2
	s_add_u32 s31, s20, 0x80
	s_addc_u32 s23, s21, 0
	s_add_i32 s89, 0, 0x10000
	s_cmp_eq_u32 s90, s22
	s_cselect_b32 s23, s3, s23
	s_cselect_b32 s22, s2, s31
	v_add_u32_e32 v146, s89, v148
	s_cselect_b32 s63, s19, vcc_hi
	s_cselect_b32 s62, s18, vcc_lo
	s_add_i32 s31, 0, 0x14000
	ds_read_b128 v[138:141], v146
	ds_read_b128 v[142:145], v146 offset:1024
	ds_read_b128 v[152:155], v146 offset:2048
	ds_read_b128 v[156:159], v146 offset:3072
	v_add_u32_e32 v146, s31, v148
	ds_read_b128 v[160:163], v146
	ds_read_b128 v[164:167], v146 offset:1024
	ds_read_b128 v[168:171], v146 offset:2048
	ds_read_b128 v[172:175], v146 offset:3072
	v_lshl_add_u64 v[146:147], s[20:21], 0, v[134:135]
	s_add_i32 m0, s67, 0xc000
	ds_read_b128 v[176:179], v150
	ds_read_b128 v[180:183], v150 offset:1024
	ds_read_b128 v[184:187], v150 offset:2048
	ds_read_b128 v[188:191], v150 offset:3072
	ds_read_b128 v[192:195], v150 offset:4096
	ds_read_b128 v[196:199], v150 offset:5120
	ds_read_b128 v[200:203], v150 offset:6144
	ds_read_b128 v[214:217], v150 offset:7168
	global_load_lds_dwordx4 v[146:147], off
	v_lshl_add_u64 v[146:147], s[20:21], 0, v[136:137]
	s_add_i32 m0, s67, 0xe000
	s_nop 0
	global_load_lds_dwordx4 v[146:147], off
	s_waitcnt vmcnt(8)
	s_waitcnt lgkmcnt(0)
	s_barrier
	s_setprio 1
	s_waitcnt lgkmcnt(0)
	v_mfma_f32_16x16x32_bf16 v[126:129], v[138:141], v[176:179], 0
	v_mfma_f32_16x16x32_bf16 v[94:97], v[152:155], v[176:179], 0
	v_mfma_f32_16x16x32_bf16 v[122:125], v[138:141], v[184:187], 0
	v_mfma_f32_16x16x32_bf16 v[90:93], v[152:155], v[184:187], 0
	v_mfma_f32_16x16x32_bf16 v[118:121], v[138:141], v[192:195], 0
	v_mfma_f32_16x16x32_bf16 v[86:89], v[152:155], v[192:195], 0
	v_mfma_f32_16x16x32_bf16 v[114:117], v[138:141], v[200:203], 0
	v_mfma_f32_16x16x32_bf16 v[82:85], v[152:155], v[200:203], 0
	v_mfma_f32_16x16x32_bf16 v[126:129], v[142:145], v[180:183], v[126:129]
	v_mfma_f32_16x16x32_bf16 v[94:97], v[156:159], v[180:183], v[94:97]
	v_mfma_f32_16x16x32_bf16 v[122:125], v[142:145], v[188:191], v[122:125]
	v_mfma_f32_16x16x32_bf16 v[90:93], v[156:159], v[188:191], v[90:93]
	v_mfma_f32_16x16x32_bf16 v[118:121], v[142:145], v[196:199], v[118:121]
	v_mfma_f32_16x16x32_bf16 v[86:89], v[156:159], v[196:199], v[86:89]
	v_mfma_f32_16x16x32_bf16 v[114:117], v[142:145], v[214:217], v[114:117]
	v_mfma_f32_16x16x32_bf16 v[82:85], v[156:159], v[214:217], v[82:85]
	s_setprio 0
	s_setprio 1
	v_mfma_f32_16x16x32_bf16 v[62:65], v[160:163], v[176:179], 0
	v_mfma_f32_16x16x32_bf16 v[30:33], v[168:171], v[176:179], 0
	v_mfma_f32_16x16x32_bf16 v[58:61], v[160:163], v[184:187], 0
	v_mfma_f32_16x16x32_bf16 v[26:29], v[168:171], v[184:187], 0
	v_mfma_f32_16x16x32_bf16 v[54:57], v[160:163], v[192:195], 0
	v_mfma_f32_16x16x32_bf16 v[22:25], v[168:171], v[192:195], 0
	v_mfma_f32_16x16x32_bf16 v[50:53], v[160:163], v[200:203], 0
	v_mfma_f32_16x16x32_bf16 v[18:21], v[168:171], v[200:203], 0
	v_mfma_f32_16x16x32_bf16 v[62:65], v[164:167], v[180:183], v[62:65]
	v_mfma_f32_16x16x32_bf16 v[30:33], v[172:175], v[180:183], v[30:33]
	v_mfma_f32_16x16x32_bf16 v[58:61], v[164:167], v[188:191], v[58:61]
	v_mfma_f32_16x16x32_bf16 v[26:29], v[172:175], v[188:191], v[26:29]
	v_mfma_f32_16x16x32_bf16 v[54:57], v[164:167], v[196:199], v[54:57]
	v_mfma_f32_16x16x32_bf16 v[22:25], v[172:175], v[196:199], v[22:25]
	v_mfma_f32_16x16x32_bf16 v[50:53], v[164:167], v[214:217], v[50:53]
	v_mfma_f32_16x16x32_bf16 v[18:21], v[172:175], v[214:217], v[18:21]
	s_setprio 0
	s_barrier
	s_add_i32 s89, s89, s56
	v_lshl_add_u64 v[146:147], s[62:63], 0, v[132:133]
	s_mov_b32 m0, s89
	ds_read_b128 v[176:179], v150 offset:16384
	ds_read_b128 v[180:183], v150 offset:17408
	ds_read_b128 v[184:187], v150 offset:18432
	ds_read_b128 v[188:191], v150 offset:19456
	ds_read_b128 v[192:195], v150 offset:20480
	ds_read_b128 v[196:199], v150 offset:21504
	ds_read_b128 v[200:203], v150 offset:22528
	ds_read_b128 v[214:217], v150 offset:23552
	global_load_lds_dwordx4 v[146:147], off
	s_add_i32 m0, s89, 0x2000
	v_lshl_add_u64 v[204:205], s[62:63], 0, v[130:131]
	s_add_u32 s62, s62, s8
	s_addc_u32 s63, s63, s9
	s_add_i32 s31, s31, s56
	global_load_lds_dwordx4 v[204:205], off
	v_lshl_add_u64 v[218:219], s[62:63], 0, v[132:133]
	s_mov_b32 m0, s31
	v_lshl_add_u64 v[220:221], s[62:63], 0, v[130:131]
	global_load_lds_dwordx4 v[218:219], off
	s_add_i32 m0, s31, 0x2000
	v_lshl_add_u64 v[222:223], s[22:23], 0, v[132:133]
	global_load_lds_dwordx4 v[220:221], off
	s_mov_b32 m0, s67
	v_lshl_add_u64 v[224:225], s[22:23], 0, v[130:131]
	global_load_lds_dwordx4 v[222:223], off
	s_mov_b32 m0, s72
	s_nop 0
	global_load_lds_dwordx4 v[224:225], off
	s_waitcnt vmcnt(8)
	s_waitcnt lgkmcnt(0)
	s_barrier
	s_setprio 1
	s_waitcnt lgkmcnt(0)
	v_mfma_f32_16x16x32_bf16 v[110:113], v[138:141], v[176:179], 0
	v_mfma_f32_16x16x32_bf16 v[78:81], v[152:155], v[176:179], 0
	v_mfma_f32_16x16x32_bf16 v[106:109], v[138:141], v[184:187], 0
	v_mfma_f32_16x16x32_bf16 v[74:77], v[152:155], v[184:187], 0
	v_mfma_f32_16x16x32_bf16 v[102:105], v[138:141], v[192:195], 0
	v_mfma_f32_16x16x32_bf16 v[70:73], v[152:155], v[192:195], 0
	v_mfma_f32_16x16x32_bf16 v[98:101], v[138:141], v[200:203], 0
	v_mfma_f32_16x16x32_bf16 v[66:69], v[152:155], v[200:203], 0
	v_mfma_f32_16x16x32_bf16 v[110:113], v[142:145], v[180:183], v[110:113]
	v_mfma_f32_16x16x32_bf16 v[78:81], v[156:159], v[180:183], v[78:81]
	v_mfma_f32_16x16x32_bf16 v[106:109], v[142:145], v[188:191], v[106:109]
	v_mfma_f32_16x16x32_bf16 v[74:77], v[156:159], v[188:191], v[74:77]
	v_mfma_f32_16x16x32_bf16 v[102:105], v[142:145], v[196:199], v[102:105]
	v_mfma_f32_16x16x32_bf16 v[70:73], v[156:159], v[196:199], v[70:73]
	v_mfma_f32_16x16x32_bf16 v[98:101], v[142:145], v[214:217], v[98:101]
	v_mfma_f32_16x16x32_bf16 v[66:69], v[156:159], v[214:217], v[66:69]
	s_setprio 0
	s_setprio 1
	v_mfma_f32_16x16x32_bf16 v[46:49], v[160:163], v[176:179], 0
	v_mfma_f32_16x16x32_bf16 v[14:17], v[168:171], v[176:179], 0
	v_mfma_f32_16x16x32_bf16 v[42:45], v[160:163], v[184:187], 0
	v_mfma_f32_16x16x32_bf16 v[10:13], v[168:171], v[184:187], 0
	v_mfma_f32_16x16x32_bf16 v[38:41], v[160:163], v[192:195], 0
	v_mfma_f32_16x16x32_bf16 v[6:9], v[168:171], v[192:195], 0
	v_mfma_f32_16x16x32_bf16 v[34:37], v[160:163], v[200:203], 0
	v_mfma_f32_16x16x32_bf16 v[2:5], v[168:171], v[200:203], 0
	v_mfma_f32_16x16x32_bf16 v[46:49], v[164:167], v[180:183], v[46:49]
	v_mfma_f32_16x16x32_bf16 v[14:17], v[172:175], v[180:183], v[14:17]
	v_mfma_f32_16x16x32_bf16 v[42:45], v[164:167], v[188:191], v[42:45]
	v_mfma_f32_16x16x32_bf16 v[10:13], v[172:175], v[188:191], v[10:13]
	v_mfma_f32_16x16x32_bf16 v[38:41], v[164:167], v[196:199], v[38:41]
	v_mfma_f32_16x16x32_bf16 v[6:9], v[172:175], v[196:199], v[6:9]
	v_mfma_f32_16x16x32_bf16 v[34:37], v[164:167], v[214:217], v[34:37]
	v_mfma_f32_16x16x32_bf16 v[2:5], v[172:175], v[214:217], v[2:5]
	s_setprio 0
	s_barrier
	s_add_i32 s31, 0, 0x18000
	v_add_u32_e32 v151, s31, v148
	s_add_i32 s62, 0, 0x1c000
	ds_read_b128 v[138:141], v151
	ds_read_b128 v[142:145], v151 offset:1024
	ds_read_b128 v[152:155], v151 offset:2048
	ds_read_b128 v[156:159], v151 offset:3072
	v_add_u32_e32 v151, s62, v148
	ds_read_b128 v[160:163], v151
	ds_read_b128 v[164:167], v151 offset:1024
	ds_read_b128 v[168:171], v151 offset:2048
	ds_read_b128 v[172:175], v151 offset:3072
	s_add_u32 s22, s22, s8
	s_addc_u32 s23, s23, s9
	s_mov_b32 m0, s73
	v_lshl_add_u64 v[226:227], s[22:23], 0, v[132:133]
	ds_read_b128 v[176:179], v150 offset:32768
	ds_read_b128 v[180:183], v150 offset:33792
	ds_read_b128 v[184:187], v150 offset:34816
	ds_read_b128 v[188:191], v150 offset:35840
	ds_read_b128 v[192:195], v150 offset:36864
	ds_read_b128 v[196:199], v150 offset:37888
	ds_read_b128 v[200:203], v150 offset:38912
	ds_read_b128 v[214:217], v150 offset:39936
	global_load_lds_dwordx4 v[226:227], off
	v_lshl_add_u64 v[226:227], s[22:23], 0, v[130:131]
	s_mov_b32 m0, s74
	s_nop 0
	global_load_lds_dwordx4 v[226:227], off
	s_waitcnt vmcnt(8)
	s_waitcnt lgkmcnt(0)
	s_barrier
	s_setprio 1
	s_waitcnt lgkmcnt(0)
	v_mfma_f32_16x16x32_bf16 v[126:129], v[138:141], v[176:179], v[126:129]
	v_mfma_f32_16x16x32_bf16 v[94:97], v[152:155], v[176:179], v[94:97]
	v_mfma_f32_16x16x32_bf16 v[122:125], v[138:141], v[184:187], v[122:125]
	v_mfma_f32_16x16x32_bf16 v[90:93], v[152:155], v[184:187], v[90:93]
	v_mfma_f32_16x16x32_bf16 v[118:121], v[138:141], v[192:195], v[118:121]
	v_mfma_f32_16x16x32_bf16 v[86:89], v[152:155], v[192:195], v[86:89]
	v_mfma_f32_16x16x32_bf16 v[114:117], v[138:141], v[200:203], v[114:117]
	v_mfma_f32_16x16x32_bf16 v[82:85], v[152:155], v[200:203], v[82:85]
	v_mfma_f32_16x16x32_bf16 v[126:129], v[142:145], v[180:183], v[126:129]
	v_mfma_f32_16x16x32_bf16 v[94:97], v[156:159], v[180:183], v[94:97]
	v_mfma_f32_16x16x32_bf16 v[122:125], v[142:145], v[188:191], v[122:125]
	v_mfma_f32_16x16x32_bf16 v[90:93], v[156:159], v[188:191], v[90:93]
	v_mfma_f32_16x16x32_bf16 v[118:121], v[142:145], v[196:199], v[118:121]
	v_mfma_f32_16x16x32_bf16 v[86:89], v[156:159], v[196:199], v[86:89]
	v_mfma_f32_16x16x32_bf16 v[114:117], v[142:145], v[214:217], v[114:117]
	v_mfma_f32_16x16x32_bf16 v[82:85], v[156:159], v[214:217], v[82:85]
	s_setprio 0
	s_setprio 1
	v_mfma_f32_16x16x32_bf16 v[62:65], v[160:163], v[176:179], v[62:65]
	v_mfma_f32_16x16x32_bf16 v[30:33], v[168:171], v[176:179], v[30:33]
	v_mfma_f32_16x16x32_bf16 v[58:61], v[160:163], v[184:187], v[58:61]
	v_mfma_f32_16x16x32_bf16 v[26:29], v[168:171], v[184:187], v[26:29]
	v_mfma_f32_16x16x32_bf16 v[54:57], v[160:163], v[192:195], v[54:57]
	v_mfma_f32_16x16x32_bf16 v[22:25], v[168:171], v[192:195], v[22:25]
	v_mfma_f32_16x16x32_bf16 v[50:53], v[160:163], v[200:203], v[50:53]
	v_mfma_f32_16x16x32_bf16 v[18:21], v[168:171], v[200:203], v[18:21]
	v_mfma_f32_16x16x32_bf16 v[62:65], v[164:167], v[180:183], v[62:65]
	v_mfma_f32_16x16x32_bf16 v[30:33], v[172:175], v[180:183], v[30:33]
	v_mfma_f32_16x16x32_bf16 v[58:61], v[164:167], v[188:191], v[58:61]
	v_mfma_f32_16x16x32_bf16 v[26:29], v[172:175], v[188:191], v[26:29]
	v_mfma_f32_16x16x32_bf16 v[54:57], v[164:167], v[196:199], v[54:57]
	v_mfma_f32_16x16x32_bf16 v[22:25], v[172:175], v[196:199], v[22:25]
	v_mfma_f32_16x16x32_bf16 v[50:53], v[164:167], v[214:217], v[50:53]
	v_mfma_f32_16x16x32_bf16 v[18:21], v[172:175], v[214:217], v[18:21]
	s_setprio 0
	s_barrier
	s_add_i32 s22, s31, s56
	v_lshl_add_u64 v[146:147], v[146:147], 0, s[60:61]
	s_mov_b32 m0, s22
	ds_read_b128 v[176:179], v150 offset:49152
	ds_read_b128 v[180:183], v150 offset:50176
	ds_read_b128 v[184:187], v150 offset:51200
	ds_read_b128 v[188:191], v150 offset:52224
	ds_read_b128 v[192:195], v150 offset:53248
	ds_read_b128 v[196:199], v150 offset:54272
	ds_read_b128 v[200:203], v150 offset:55296
	ds_read_b128 v[214:217], v150 offset:56320
	global_load_lds_dwordx4 v[146:147], off
	v_lshl_add_u64 v[146:147], v[204:205], 0, s[60:61]
	s_add_i32 m0, s22, 0x2000
	s_add_i32 s22, s62, s56
	global_load_lds_dwordx4 v[146:147], off
	v_lshl_add_u64 v[146:147], v[218:219], 0, s[60:61]
	s_mov_b32 m0, s22
	s_nop 0
	global_load_lds_dwordx4 v[146:147], off
	v_lshl_add_u64 v[146:147], v[220:221], 0, s[60:61]
	s_add_i32 m0, s22, 0x2000
	s_nop 0
	global_load_lds_dwordx4 v[146:147], off
	v_lshl_add_u64 v[146:147], v[222:223], 0, s[60:61]
	s_mov_b32 m0, s77
	s_nop 0
	global_load_lds_dwordx4 v[146:147], off
	v_lshl_add_u64 v[146:147], v[224:225], 0, s[60:61]
	s_mov_b32 m0, s78
	s_nop 0
	global_load_lds_dwordx4 v[146:147], off
	s_waitcnt vmcnt(8)
	s_waitcnt lgkmcnt(0)
	s_barrier
	s_setprio 1
	s_waitcnt lgkmcnt(0)
	v_mfma_f32_16x16x32_bf16 v[110:113], v[138:141], v[176:179], v[110:113]
	v_mfma_f32_16x16x32_bf16 v[78:81], v[152:155], v[176:179], v[78:81]
	v_mfma_f32_16x16x32_bf16 v[106:109], v[138:141], v[184:187], v[106:109]
	v_mfma_f32_16x16x32_bf16 v[74:77], v[152:155], v[184:187], v[74:77]
	v_mfma_f32_16x16x32_bf16 v[102:105], v[138:141], v[192:195], v[102:105]
	v_mfma_f32_16x16x32_bf16 v[70:73], v[152:155], v[192:195], v[70:73]
	v_mfma_f32_16x16x32_bf16 v[98:101], v[138:141], v[200:203], v[98:101]
	v_mfma_f32_16x16x32_bf16 v[66:69], v[152:155], v[200:203], v[66:69]
	v_mfma_f32_16x16x32_bf16 v[110:113], v[142:145], v[180:183], v[110:113]
	v_mfma_f32_16x16x32_bf16 v[78:81], v[156:159], v[180:183], v[78:81]
	v_mfma_f32_16x16x32_bf16 v[106:109], v[142:145], v[188:191], v[106:109]
	v_mfma_f32_16x16x32_bf16 v[74:77], v[156:159], v[188:191], v[74:77]
	v_mfma_f32_16x16x32_bf16 v[102:105], v[142:145], v[196:199], v[102:105]
	v_mfma_f32_16x16x32_bf16 v[70:73], v[156:159], v[196:199], v[70:73]
	v_mfma_f32_16x16x32_bf16 v[98:101], v[142:145], v[214:217], v[98:101]
	v_mfma_f32_16x16x32_bf16 v[66:69], v[156:159], v[214:217], v[66:69]
	s_setprio 0
	s_setprio 1
	v_mfma_f32_16x16x32_bf16 v[46:49], v[160:163], v[176:179], v[46:49]
	v_mfma_f32_16x16x32_bf16 v[14:17], v[168:171], v[176:179], v[14:17]
	v_mfma_f32_16x16x32_bf16 v[42:45], v[160:163], v[184:187], v[42:45]
	v_mfma_f32_16x16x32_bf16 v[10:13], v[168:171], v[184:187], v[10:13]
	v_mfma_f32_16x16x32_bf16 v[38:41], v[160:163], v[192:195], v[38:41]
	v_mfma_f32_16x16x32_bf16 v[6:9], v[168:171], v[192:195], v[6:9]
	v_mfma_f32_16x16x32_bf16 v[34:37], v[160:163], v[200:203], v[34:37]
	v_mfma_f32_16x16x32_bf16 v[2:5], v[168:171], v[200:203], v[2:5]
	v_mfma_f32_16x16x32_bf16 v[46:49], v[164:167], v[180:183], v[46:49]
	v_mfma_f32_16x16x32_bf16 v[14:17], v[172:175], v[180:183], v[14:17]
	v_mfma_f32_16x16x32_bf16 v[42:45], v[164:167], v[188:191], v[42:45]
	v_mfma_f32_16x16x32_bf16 v[10:13], v[172:175], v[188:191], v[10:13]
	v_mfma_f32_16x16x32_bf16 v[38:41], v[164:167], v[196:199], v[38:41]
	v_mfma_f32_16x16x32_bf16 v[6:9], v[172:175], v[196:199], v[6:9]
	v_mfma_f32_16x16x32_bf16 v[34:37], v[164:167], v[214:217], v[34:37]
	v_mfma_f32_16x16x32_bf16 v[2:5], v[172:175], v[214:217], v[2:5]
	s_setprio 0
	s_barrier
	s_add_u32 s20, s20, 0x100
	s_addc_u32 s21, s21, 0
	s_add_u32 vcc_lo, vcc_lo, 0x100
	s_addc_u32 vcc_hi, vcc_hi, 0
	s_cmp_ge_i32 s88, s79
	s_mov_b32 s22, s88
	s_cbranch_scc1 .LBB0_361
	.p2alignl 6, 3212836864

.Lzgo_3:
	s_add_u32 s18, s18, 0x80
	s_addc_u32 s19, s19, 0
	s_add_u32 s71, s20, 0x100
	s_addc_u32 s72, s21, 0
	s_mov_b32 s20, 0
	s_add_i32 s73, s20, 2
	s_add_u32 s31, s18, 0x80
	s_addc_u32 s21, s19, 0
	s_add_i32 s74, 0, 0x10000
	s_cmp_eq_u32 s11, s20
	s_cselect_b32 s21, s3, s21
	s_cselect_b32 s20, s2, s31
	v_add_u32_e32 v145, s74, v142
	s_cselect_b32 s63, s17, s72
	s_cselect_b32 s62, s16, s71
	s_add_i32 s31, 0, 0x14000
	ds_read_b128 v[146:149], v145
	ds_read_b128 v[150:153], v145 offset:1024
	ds_read_b128 v[154:157], v145 offset:2048
	ds_read_b128 v[158:161], v145 offset:3072
	v_add_u32_e32 v145, s31, v142
	ds_read_b128 v[162:165], v145
	ds_read_b128 v[166:169], v145 offset:1024
	ds_read_b128 v[170:173], v145 offset:2048
	ds_read_b128 v[174:177], v145 offset:3072
	v_lshl_add_u64 v[218:219], s[18:19], 0, v[138:139]
	s_add_i32 m0, s23, 0xc000
	ds_read_b128 v[178:181], v144
	ds_read_b128 v[182:185], v144 offset:1024
	ds_read_b128 v[186:189], v144 offset:2048
	ds_read_b128 v[190:193], v144 offset:3072
	ds_read_b128 v[194:197], v144 offset:4096
	ds_read_b128 v[198:201], v144 offset:5120
	ds_read_b128 v[202:205], v144 offset:6144
	ds_read_b128 v[214:217], v144 offset:7168
	global_load_lds_dwordx4 v[218:219], off
	v_lshl_add_u64 v[218:219], s[18:19], 0, v[140:141]
	s_add_i32 m0, s23, 0xe000
	s_nop 0
	global_load_lds_dwordx4 v[218:219], off
	s_waitcnt vmcnt(8)
	s_waitcnt lgkmcnt(0)
	s_barrier
	s_setprio 1
	s_waitcnt lgkmcnt(0)
	v_mfma_f32_16x16x32_bf16 v[122:125], v[146:149], v[178:181], 0
	v_mfma_f32_16x16x32_bf16 v[126:129], v[154:157], v[178:181], 0
	v_mfma_f32_16x16x32_bf16 v[118:121], v[146:149], v[186:189], 0
	v_mfma_f32_16x16x32_bf16 v[114:117], v[154:157], v[186:189], 0
	v_mfma_f32_16x16x32_bf16 v[110:113], v[146:149], v[194:197], 0
	v_mfma_f32_16x16x32_bf16 v[106:109], v[154:157], v[194:197], 0
	v_mfma_f32_16x16x32_bf16 v[102:105], v[146:149], v[202:205], 0
	v_mfma_f32_16x16x32_bf16 v[98:101], v[154:157], v[202:205], 0
	v_mfma_f32_16x16x32_bf16 v[122:125], v[150:153], v[182:185], v[122:125]
	v_mfma_f32_16x16x32_bf16 v[126:129], v[158:161], v[182:185], v[126:129]
	v_mfma_f32_16x16x32_bf16 v[118:121], v[150:153], v[190:193], v[118:121]
	v_mfma_f32_16x16x32_bf16 v[114:117], v[158:161], v[190:193], v[114:117]
	v_mfma_f32_16x16x32_bf16 v[110:113], v[150:153], v[198:201], v[110:113]
	v_mfma_f32_16x16x32_bf16 v[106:109], v[158:161], v[198:201], v[106:109]
	v_mfma_f32_16x16x32_bf16 v[102:105], v[150:153], v[214:217], v[102:105]
	v_mfma_f32_16x16x32_bf16 v[98:101], v[158:161], v[214:217], v[98:101]
	s_setprio 0
	s_setprio 1
	v_mfma_f32_16x16x32_bf16 v[62:65], v[162:165], v[178:181], 0
	v_mfma_f32_16x16x32_bf16 v[58:61], v[170:173], v[178:181], 0
	v_mfma_f32_16x16x32_bf16 v[54:57], v[162:165], v[186:189], 0
	v_mfma_f32_16x16x32_bf16 v[50:53], v[170:173], v[186:189], 0
	v_mfma_f32_16x16x32_bf16 v[46:49], v[162:165], v[194:197], 0
	v_mfma_f32_16x16x32_bf16 v[42:45], v[170:173], v[194:197], 0
	v_mfma_f32_16x16x32_bf16 v[38:41], v[162:165], v[202:205], 0
	v_mfma_f32_16x16x32_bf16 v[34:37], v[170:173], v[202:205], 0
	v_mfma_f32_16x16x32_bf16 v[62:65], v[166:169], v[182:185], v[62:65]
	v_mfma_f32_16x16x32_bf16 v[58:61], v[174:177], v[182:185], v[58:61]
	v_mfma_f32_16x16x32_bf16 v[54:57], v[166:169], v[190:193], v[54:57]
	v_mfma_f32_16x16x32_bf16 v[50:53], v[174:177], v[190:193], v[50:53]
	v_mfma_f32_16x16x32_bf16 v[46:49], v[166:169], v[198:201], v[46:49]
	v_mfma_f32_16x16x32_bf16 v[42:45], v[174:177], v[198:201], v[42:45]
	v_mfma_f32_16x16x32_bf16 v[38:41], v[166:169], v[214:217], v[38:41]
	v_mfma_f32_16x16x32_bf16 v[34:37], v[174:177], v[214:217], v[34:37]
	s_setprio 0
	s_barrier
	s_add_i32 s74, s74, s22
	v_lshl_add_u64 v[218:219], s[62:63], 0, v[134:135]
	s_mov_b32 m0, s74
	ds_read_b128 v[178:181], v144 offset:16384
	ds_read_b128 v[182:185], v144 offset:17408
	ds_read_b128 v[186:189], v144 offset:18432
	ds_read_b128 v[190:193], v144 offset:19456
	ds_read_b128 v[194:197], v144 offset:20480
	ds_read_b128 v[198:201], v144 offset:21504
	ds_read_b128 v[202:205], v144 offset:22528
	ds_read_b128 v[214:217], v144 offset:23552
	global_load_lds_dwordx4 v[218:219], off
	s_add_i32 m0, s74, 0x2000
	v_lshl_add_u64 v[220:221], s[62:63], 0, v[130:131]
	s_add_u32 s62, s62, s4
	s_addc_u32 s63, s63, s5
	s_add_i32 s31, s31, s22
	global_load_lds_dwordx4 v[220:221], off
	v_lshl_add_u64 v[222:223], s[62:63], 0, v[134:135]
	s_mov_b32 m0, s31
	v_lshl_add_u64 v[224:225], s[62:63], 0, v[130:131]
	global_load_lds_dwordx4 v[222:223], off
	s_add_i32 m0, s31, 0x2000
	v_lshl_add_u64 v[226:227], s[20:21], 0, v[136:137]
	global_load_lds_dwordx4 v[224:225], off
	s_mov_b32 m0, s23
	v_lshl_add_u64 v[236:237], s[20:21], 0, v[132:133]
	global_load_lds_dwordx4 v[226:227], off
	s_mov_b32 m0, s52
	s_nop 0
	global_load_lds_dwordx4 v[236:237], off
	s_waitcnt vmcnt(8)
	s_waitcnt lgkmcnt(0)
	s_barrier
	s_setprio 1
	s_waitcnt lgkmcnt(0)
	v_mfma_f32_16x16x32_bf16 v[94:97], v[146:149], v[178:181], 0
	v_mfma_f32_16x16x32_bf16 v[90:93], v[154:157], v[178:181], 0
	v_mfma_f32_16x16x32_bf16 v[86:89], v[146:149], v[186:189], 0
	v_mfma_f32_16x16x32_bf16 v[82:85], v[154:157], v[186:189], 0
	v_mfma_f32_16x16x32_bf16 v[78:81], v[146:149], v[194:197], 0
	v_mfma_f32_16x16x32_bf16 v[74:77], v[154:157], v[194:197], 0
	v_mfma_f32_16x16x32_bf16 v[70:73], v[146:149], v[202:205], 0
	v_mfma_f32_16x16x32_bf16 v[66:69], v[154:157], v[202:205], 0
	v_mfma_f32_16x16x32_bf16 v[94:97], v[150:153], v[182:185], v[94:97]
	v_mfma_f32_16x16x32_bf16 v[90:93], v[158:161], v[182:185], v[90:93]
	v_mfma_f32_16x16x32_bf16 v[86:89], v[150:153], v[190:193], v[86:89]
	v_mfma_f32_16x16x32_bf16 v[82:85], v[158:161], v[190:193], v[82:85]
	v_mfma_f32_16x16x32_bf16 v[78:81], v[150:153], v[198:201], v[78:81]
	v_mfma_f32_16x16x32_bf16 v[74:77], v[158:161], v[198:201], v[74:77]
	v_mfma_f32_16x16x32_bf16 v[70:73], v[150:153], v[214:217], v[70:73]
	v_mfma_f32_16x16x32_bf16 v[66:69], v[158:161], v[214:217], v[66:69]
	s_setprio 0
	s_setprio 1
	v_mfma_f32_16x16x32_bf16 v[30:33], v[162:165], v[178:181], 0
	v_mfma_f32_16x16x32_bf16 v[26:29], v[170:173], v[178:181], 0
	v_mfma_f32_16x16x32_bf16 v[22:25], v[162:165], v[186:189], 0
	v_mfma_f32_16x16x32_bf16 v[18:21], v[170:173], v[186:189], 0
	v_mfma_f32_16x16x32_bf16 v[14:17], v[162:165], v[194:197], 0
	v_mfma_f32_16x16x32_bf16 v[10:13], v[170:173], v[194:197], 0
	v_mfma_f32_16x16x32_bf16 v[6:9], v[162:165], v[202:205], 0
	v_mfma_f32_16x16x32_bf16 v[2:5], v[170:173], v[202:205], 0
	v_mfma_f32_16x16x32_bf16 v[30:33], v[166:169], v[182:185], v[30:33]
	v_mfma_f32_16x16x32_bf16 v[26:29], v[174:177], v[182:185], v[26:29]
	v_mfma_f32_16x16x32_bf16 v[22:25], v[166:169], v[190:193], v[22:25]
	v_mfma_f32_16x16x32_bf16 v[18:21], v[174:177], v[190:193], v[18:21]
	v_mfma_f32_16x16x32_bf16 v[14:17], v[166:169], v[198:201], v[14:17]
	v_mfma_f32_16x16x32_bf16 v[10:13], v[174:177], v[198:201], v[10:13]
	v_mfma_f32_16x16x32_bf16 v[6:9], v[166:169], v[214:217], v[6:9]
	v_mfma_f32_16x16x32_bf16 v[2:5], v[174:177], v[214:217], v[2:5]
	s_setprio 0
	s_barrier
	s_add_i32 s31, 0, 0x18000
	v_add_u32_e32 v145, s31, v142
	s_add_i32 s62, 0, 0x1c000
	ds_read_b128 v[146:149], v145
	ds_read_b128 v[150:153], v145 offset:1024
	ds_read_b128 v[154:157], v145 offset:2048
	ds_read_b128 v[158:161], v145 offset:3072
	v_add_u32_e32 v145, s62, v142
	ds_read_b128 v[162:165], v145
	ds_read_b128 v[166:169], v145 offset:1024
	ds_read_b128 v[170:173], v145 offset:2048
	ds_read_b128 v[174:177], v145 offset:3072
	s_add_u32 s20, s20, s4
	s_addc_u32 s21, s21, s5
	s_mov_b32 m0, s53
	v_lshl_add_u64 v[238:239], s[20:21], 0, v[136:137]
	ds_read_b128 v[178:181], v144 offset:32768
	ds_read_b128 v[182:185], v144 offset:33792
	ds_read_b128 v[186:189], v144 offset:34816
	ds_read_b128 v[190:193], v144 offset:35840
	ds_read_b128 v[194:197], v144 offset:36864
	ds_read_b128 v[198:201], v144 offset:37888
	ds_read_b128 v[202:205], v144 offset:38912
	ds_read_b128 v[214:217], v144 offset:39936
	global_load_lds_dwordx4 v[238:239], off
	v_lshl_add_u64 v[238:239], s[20:21], 0, v[132:133]
	s_mov_b32 m0, s56
	s_nop 0
	global_load_lds_dwordx4 v[238:239], off
	s_waitcnt vmcnt(8)
	s_waitcnt lgkmcnt(0)
	s_barrier
	s_setprio 1
	s_waitcnt lgkmcnt(0)
	v_mfma_f32_16x16x32_bf16 v[122:125], v[146:149], v[178:181], v[122:125]
	v_mfma_f32_16x16x32_bf16 v[126:129], v[154:157], v[178:181], v[126:129]
	v_mfma_f32_16x16x32_bf16 v[118:121], v[146:149], v[186:189], v[118:121]
	v_mfma_f32_16x16x32_bf16 v[114:117], v[154:157], v[186:189], v[114:117]
	v_mfma_f32_16x16x32_bf16 v[110:113], v[146:149], v[194:197], v[110:113]
	v_mfma_f32_16x16x32_bf16 v[106:109], v[154:157], v[194:197], v[106:109]
	v_mfma_f32_16x16x32_bf16 v[102:105], v[146:149], v[202:205], v[102:105]
	v_mfma_f32_16x16x32_bf16 v[98:101], v[154:157], v[202:205], v[98:101]
	v_mfma_f32_16x16x32_bf16 v[122:125], v[150:153], v[182:185], v[122:125]
	v_mfma_f32_16x16x32_bf16 v[126:129], v[158:161], v[182:185], v[126:129]
	v_mfma_f32_16x16x32_bf16 v[118:121], v[150:153], v[190:193], v[118:121]
	v_mfma_f32_16x16x32_bf16 v[114:117], v[158:161], v[190:193], v[114:117]
	v_mfma_f32_16x16x32_bf16 v[110:113], v[150:153], v[198:201], v[110:113]
	v_mfma_f32_16x16x32_bf16 v[106:109], v[158:161], v[198:201], v[106:109]
	v_mfma_f32_16x16x32_bf16 v[102:105], v[150:153], v[214:217], v[102:105]
	v_mfma_f32_16x16x32_bf16 v[98:101], v[158:161], v[214:217], v[98:101]
	s_setprio 0
	s_setprio 1
	v_mfma_f32_16x16x32_bf16 v[62:65], v[162:165], v[178:181], v[62:65]
	v_mfma_f32_16x16x32_bf16 v[58:61], v[170:173], v[178:181], v[58:61]
	v_mfma_f32_16x16x32_bf16 v[54:57], v[162:165], v[186:189], v[54:57]
	v_mfma_f32_16x16x32_bf16 v[50:53], v[170:173], v[186:189], v[50:53]
	v_mfma_f32_16x16x32_bf16 v[46:49], v[162:165], v[194:197], v[46:49]
	v_mfma_f32_16x16x32_bf16 v[42:45], v[170:173], v[194:197], v[42:45]
	v_mfma_f32_16x16x32_bf16 v[38:41], v[162:165], v[202:205], v[38:41]
	v_mfma_f32_16x16x32_bf16 v[34:37], v[170:173], v[202:205], v[34:37]
	v_mfma_f32_16x16x32_bf16 v[62:65], v[166:169], v[182:185], v[62:65]
	v_mfma_f32_16x16x32_bf16 v[58:61], v[174:177], v[182:185], v[58:61]
	v_mfma_f32_16x16x32_bf16 v[54:57], v[166:169], v[190:193], v[54:57]
	v_mfma_f32_16x16x32_bf16 v[50:53], v[174:177], v[190:193], v[50:53]
	v_mfma_f32_16x16x32_bf16 v[46:49], v[166:169], v[198:201], v[46:49]
	v_mfma_f32_16x16x32_bf16 v[42:45], v[174:177], v[198:201], v[42:45]
	v_mfma_f32_16x16x32_bf16 v[38:41], v[166:169], v[214:217], v[38:41]
	v_mfma_f32_16x16x32_bf16 v[34:37], v[174:177], v[214:217], v[34:37]
	s_setprio 0
	s_barrier
	s_add_i32 s20, s31, s22
	v_lshl_add_u64 v[218:219], v[218:219], 0, s[60:61]
	s_mov_b32 m0, s20
	ds_read_b128 v[178:181], v144 offset:49152
	ds_read_b128 v[182:185], v144 offset:50176
	ds_read_b128 v[186:189], v144 offset:51200
	ds_read_b128 v[190:193], v144 offset:52224
	ds_read_b128 v[194:197], v144 offset:53248
	ds_read_b128 v[198:201], v144 offset:54272
	ds_read_b128 v[202:205], v144 offset:55296
	ds_read_b128 v[214:217], v144 offset:56320
	global_load_lds_dwordx4 v[218:219], off
	v_lshl_add_u64 v[218:219], v[220:221], 0, s[60:61]
	s_add_i32 m0, s20, 0x2000
	s_add_i32 s20, s62, s22
	global_load_lds_dwordx4 v[218:219], off
	v_lshl_add_u64 v[218:219], v[222:223], 0, s[60:61]
	s_mov_b32 m0, s20
	s_nop 0
	global_load_lds_dwordx4 v[218:219], off
	v_lshl_add_u64 v[218:219], v[224:225], 0, s[60:61]
	s_add_i32 m0, s20, 0x2000
	s_nop 0
	global_load_lds_dwordx4 v[218:219], off
	v_lshl_add_u64 v[218:219], v[226:227], 0, s[60:61]
	s_mov_b32 m0, s57
	s_nop 0
	global_load_lds_dwordx4 v[218:219], off
	v_lshl_add_u64 v[218:219], v[236:237], 0, s[60:61]
	s_mov_b32 m0, s65
	s_nop 0
	global_load_lds_dwordx4 v[218:219], off
	s_waitcnt vmcnt(8)
	s_waitcnt lgkmcnt(0)
	s_barrier
	s_setprio 1
	s_waitcnt lgkmcnt(0)
	v_mfma_f32_16x16x32_bf16 v[94:97], v[146:149], v[178:181], v[94:97]
	v_mfma_f32_16x16x32_bf16 v[90:93], v[154:157], v[178:181], v[90:93]
	v_mfma_f32_16x16x32_bf16 v[86:89], v[146:149], v[186:189], v[86:89]
	v_mfma_f32_16x16x32_bf16 v[82:85], v[154:157], v[186:189], v[82:85]
	v_mfma_f32_16x16x32_bf16 v[78:81], v[146:149], v[194:197], v[78:81]
	v_mfma_f32_16x16x32_bf16 v[74:77], v[154:157], v[194:197], v[74:77]
	v_mfma_f32_16x16x32_bf16 v[70:73], v[146:149], v[202:205], v[70:73]
	v_mfma_f32_16x16x32_bf16 v[66:69], v[154:157], v[202:205], v[66:69]
	v_mfma_f32_16x16x32_bf16 v[94:97], v[150:153], v[182:185], v[94:97]
	v_mfma_f32_16x16x32_bf16 v[90:93], v[158:161], v[182:185], v[90:93]
	v_mfma_f32_16x16x32_bf16 v[86:89], v[150:153], v[190:193], v[86:89]
	v_mfma_f32_16x16x32_bf16 v[82:85], v[158:161], v[190:193], v[82:85]
	v_mfma_f32_16x16x32_bf16 v[78:81], v[150:153], v[198:201], v[78:81]
	v_mfma_f32_16x16x32_bf16 v[74:77], v[158:161], v[198:201], v[74:77]
	v_mfma_f32_16x16x32_bf16 v[70:73], v[150:153], v[214:217], v[70:73]
	v_mfma_f32_16x16x32_bf16 v[66:69], v[158:161], v[214:217], v[66:69]
	s_setprio 0
	s_setprio 1
	v_mfma_f32_16x16x32_bf16 v[30:33], v[162:165], v[178:181], v[30:33]
	v_mfma_f32_16x16x32_bf16 v[26:29], v[170:173], v[178:181], v[26:29]
	v_mfma_f32_16x16x32_bf16 v[22:25], v[162:165], v[186:189], v[22:25]
	v_mfma_f32_16x16x32_bf16 v[18:21], v[170:173], v[186:189], v[18:21]
	v_mfma_f32_16x16x32_bf16 v[14:17], v[162:165], v[194:197], v[14:17]
	v_mfma_f32_16x16x32_bf16 v[10:13], v[170:173], v[194:197], v[10:13]
	v_mfma_f32_16x16x32_bf16 v[6:9], v[162:165], v[202:205], v[6:9]
	v_mfma_f32_16x16x32_bf16 v[2:5], v[170:173], v[202:205], v[2:5]
	v_mfma_f32_16x16x32_bf16 v[30:33], v[166:169], v[182:185], v[30:33]
	v_mfma_f32_16x16x32_bf16 v[26:29], v[174:177], v[182:185], v[26:29]
	v_mfma_f32_16x16x32_bf16 v[22:25], v[166:169], v[190:193], v[22:25]
	v_mfma_f32_16x16x32_bf16 v[18:21], v[174:177], v[190:193], v[18:21]
	v_mfma_f32_16x16x32_bf16 v[14:17], v[166:169], v[198:201], v[14:17]
	v_mfma_f32_16x16x32_bf16 v[10:13], v[174:177], v[198:201], v[10:13]
	v_mfma_f32_16x16x32_bf16 v[6:9], v[166:169], v[214:217], v[6:9]
	v_mfma_f32_16x16x32_bf16 v[2:5], v[174:177], v[214:217], v[2:5]
	s_setprio 0
	s_barrier
	s_add_u32 s18, s18, 0x100
	s_addc_u32 s19, s19, 0
	s_add_u32 s71, s71, 0x100
	s_addc_u32 s72, s72, 0
	s_cmp_ge_i32 s73, s10
	s_mov_b32 s20, s73
	s_cbranch_scc1 .LBB0_493
	.p2alignl 6, 3212836864

.LBB0_932:
	s_add_i32 s5, s4, 1
	s_cmp_lg_u32 s4, 4
	s_cselect_b32 s10, s5, 0
	s_add_i32 s4, s11, 1
	s_cmp_lg_u32 s11, 4
	s_cselect_b32 s11, s4, 0
	s_cmpk_lt_u32 s9, 0x80
	s_barrier
	s_cbranch_scc0 .LBB0_771
	.p2alignl 6, 3212836864

.Lzgo_5:
	s_add_u32 s18, s18, 0x80
	s_addc_u32 s19, s19, 0
	s_add_u32 s71, s20, 0x100
	s_addc_u32 s72, s21, 0
	s_mov_b32 s20, 0
	s_add_i32 s73, s20, 2
	s_add_u32 s31, s18, 0x80
	s_addc_u32 s21, s19, 0
	s_add_i32 s74, 0, 0x10000
	s_cmp_eq_u32 s67, s20
	s_cselect_b32 s21, s3, s21
	s_cselect_b32 s20, s2, s31
	v_add_u32_e32 v149, s74, v146
	s_cselect_b32 s63, s17, s72
	s_cselect_b32 s62, s16, s71
	s_add_i32 s31, 0, 0x14000
	ds_read_b128 v[130:133], v149
	ds_read_b128 v[142:145], v149 offset:1024
	ds_read_b128 v[150:153], v149 offset:2048
	ds_read_b128 v[154:157], v149 offset:3072
	v_add_u32_e32 v149, s31, v146
	ds_read_b128 v[158:161], v149
	ds_read_b128 v[162:165], v149 offset:1024
	ds_read_b128 v[166:169], v149 offset:2048
	ds_read_b128 v[170:173], v149 offset:3072
	v_lshl_add_u64 v[214:215], s[18:19], 0, v[138:139]
	s_add_i32 m0, s23, 0xc000
	ds_read_b128 v[174:177], v148
	ds_read_b128 v[178:181], v148 offset:1024
	ds_read_b128 v[182:185], v148 offset:2048
	ds_read_b128 v[186:189], v148 offset:3072
	ds_read_b128 v[190:193], v148 offset:4096
	ds_read_b128 v[194:197], v148 offset:5120
	ds_read_b128 v[198:201], v148 offset:6144
	ds_read_b128 v[202:205], v148 offset:7168
	global_load_lds_dwordx4 v[214:215], off
	v_lshl_add_u64 v[214:215], s[18:19], 0, v[140:141]
	s_add_i32 m0, s23, 0xe000
	s_nop 0
	global_load_lds_dwordx4 v[214:215], off
	s_waitcnt vmcnt(8)
	s_waitcnt lgkmcnt(0)
	s_barrier
	s_setprio 1
	s_waitcnt lgkmcnt(0)
	v_mfma_f32_16x16x32_bf16 v[126:129], v[130:133], v[174:177], 0
	v_mfma_f32_16x16x32_bf16 v[94:97], v[150:153], v[174:177], 0
	v_mfma_f32_16x16x32_bf16 v[122:125], v[130:133], v[182:185], 0
	v_mfma_f32_16x16x32_bf16 v[90:93], v[150:153], v[182:185], 0
	v_mfma_f32_16x16x32_bf16 v[118:121], v[130:133], v[190:193], 0
	v_mfma_f32_16x16x32_bf16 v[86:89], v[150:153], v[190:193], 0
	v_mfma_f32_16x16x32_bf16 v[114:117], v[130:133], v[198:201], 0
	v_mfma_f32_16x16x32_bf16 v[82:85], v[150:153], v[198:201], 0
	v_mfma_f32_16x16x32_bf16 v[126:129], v[142:145], v[178:181], v[126:129]
	v_mfma_f32_16x16x32_bf16 v[94:97], v[154:157], v[178:181], v[94:97]
	v_mfma_f32_16x16x32_bf16 v[122:125], v[142:145], v[186:189], v[122:125]
	v_mfma_f32_16x16x32_bf16 v[90:93], v[154:157], v[186:189], v[90:93]
	v_mfma_f32_16x16x32_bf16 v[118:121], v[142:145], v[194:197], v[118:121]
	v_mfma_f32_16x16x32_bf16 v[86:89], v[154:157], v[194:197], v[86:89]
	v_mfma_f32_16x16x32_bf16 v[114:117], v[142:145], v[202:205], v[114:117]
	v_mfma_f32_16x16x32_bf16 v[82:85], v[154:157], v[202:205], v[82:85]
	s_setprio 0
	s_setprio 1
	v_mfma_f32_16x16x32_bf16 v[62:65], v[158:161], v[174:177], 0
	v_mfma_f32_16x16x32_bf16 v[30:33], v[166:169], v[174:177], 0
	v_mfma_f32_16x16x32_bf16 v[58:61], v[158:161], v[182:185], 0
	v_mfma_f32_16x16x32_bf16 v[26:29], v[166:169], v[182:185], 0
	v_mfma_f32_16x16x32_bf16 v[54:57], v[158:161], v[190:193], 0
	v_mfma_f32_16x16x32_bf16 v[22:25], v[166:169], v[190:193], 0
	v_mfma_f32_16x16x32_bf16 v[50:53], v[158:161], v[198:201], 0
	v_mfma_f32_16x16x32_bf16 v[18:21], v[166:169], v[198:201], 0
	v_mfma_f32_16x16x32_bf16 v[62:65], v[162:165], v[178:181], v[62:65]
	v_mfma_f32_16x16x32_bf16 v[30:33], v[170:173], v[178:181], v[30:33]
	v_mfma_f32_16x16x32_bf16 v[58:61], v[162:165], v[186:189], v[58:61]
	v_mfma_f32_16x16x32_bf16 v[26:29], v[170:173], v[186:189], v[26:29]
	v_mfma_f32_16x16x32_bf16 v[54:57], v[162:165], v[194:197], v[54:57]
	v_mfma_f32_16x16x32_bf16 v[22:25], v[170:173], v[194:197], v[22:25]
	v_mfma_f32_16x16x32_bf16 v[50:53], v[162:165], v[202:205], v[50:53]
	v_mfma_f32_16x16x32_bf16 v[18:21], v[170:173], v[202:205], v[18:21]
	s_setprio 0
	s_barrier
	s_add_i32 s74, s74, s22
	v_lshl_add_u64 v[214:215], s[62:63], 0, v[136:137]
	s_mov_b32 m0, s74
	ds_read_b128 v[174:177], v148 offset:16384
	ds_read_b128 v[178:181], v148 offset:17408
	ds_read_b128 v[182:185], v148 offset:18432
	ds_read_b128 v[186:189], v148 offset:19456
	ds_read_b128 v[190:193], v148 offset:20480
	ds_read_b128 v[194:197], v148 offset:21504
	ds_read_b128 v[198:201], v148 offset:22528
	ds_read_b128 v[202:205], v148 offset:23552
	global_load_lds_dwordx4 v[214:215], off
	s_add_i32 m0, s74, 0x2000
	v_lshl_add_u64 v[216:217], s[62:63], 0, v[134:135]
	s_add_u32 s62, s62, s4
	s_addc_u32 s63, s63, s5
	s_add_i32 s31, s31, s22
	global_load_lds_dwordx4 v[216:217], off
	v_lshl_add_u64 v[218:219], s[62:63], 0, v[136:137]
	s_mov_b32 m0, s31
	v_lshl_add_u64 v[220:221], s[62:63], 0, v[134:135]
	global_load_lds_dwordx4 v[218:219], off
	s_add_i32 m0, s31, 0x2000
	v_lshl_add_u64 v[222:223], s[20:21], 0, v[136:137]
	global_load_lds_dwordx4 v[220:221], off
	s_mov_b32 m0, s23
	v_lshl_add_u64 v[224:225], s[20:21], 0, v[134:135]
	global_load_lds_dwordx4 v[222:223], off
	s_mov_b32 m0, s52
	s_nop 0
	global_load_lds_dwordx4 v[224:225], off
	s_waitcnt vmcnt(8)
	s_waitcnt lgkmcnt(0)
	s_barrier
	s_setprio 1
	s_waitcnt lgkmcnt(0)
	v_mfma_f32_16x16x32_bf16 v[110:113], v[130:133], v[174:177], 0
	v_mfma_f32_16x16x32_bf16 v[78:81], v[150:153], v[174:177], 0
	v_mfma_f32_16x16x32_bf16 v[106:109], v[130:133], v[182:185], 0
	v_mfma_f32_16x16x32_bf16 v[74:77], v[150:153], v[182:185], 0
	v_mfma_f32_16x16x32_bf16 v[102:105], v[130:133], v[190:193], 0
	v_mfma_f32_16x16x32_bf16 v[70:73], v[150:153], v[190:193], 0
	v_mfma_f32_16x16x32_bf16 v[98:101], v[130:133], v[198:201], 0
	v_mfma_f32_16x16x32_bf16 v[66:69], v[150:153], v[198:201], 0
	v_mfma_f32_16x16x32_bf16 v[110:113], v[142:145], v[178:181], v[110:113]
	v_mfma_f32_16x16x32_bf16 v[78:81], v[154:157], v[178:181], v[78:81]
	v_mfma_f32_16x16x32_bf16 v[106:109], v[142:145], v[186:189], v[106:109]
	v_mfma_f32_16x16x32_bf16 v[74:77], v[154:157], v[186:189], v[74:77]
	v_mfma_f32_16x16x32_bf16 v[102:105], v[142:145], v[194:197], v[102:105]
	v_mfma_f32_16x16x32_bf16 v[70:73], v[154:157], v[194:197], v[70:73]
	v_mfma_f32_16x16x32_bf16 v[98:101], v[142:145], v[202:205], v[98:101]
	v_mfma_f32_16x16x32_bf16 v[66:69], v[154:157], v[202:205], v[66:69]
	s_setprio 0
	s_setprio 1
	v_mfma_f32_16x16x32_bf16 v[46:49], v[158:161], v[174:177], 0
	v_mfma_f32_16x16x32_bf16 v[14:17], v[166:169], v[174:177], 0
	v_mfma_f32_16x16x32_bf16 v[42:45], v[158:161], v[182:185], 0
	v_mfma_f32_16x16x32_bf16 v[10:13], v[166:169], v[182:185], 0
	v_mfma_f32_16x16x32_bf16 v[38:41], v[158:161], v[190:193], 0
	v_mfma_f32_16x16x32_bf16 v[6:9], v[166:169], v[190:193], 0
	v_mfma_f32_16x16x32_bf16 v[34:37], v[158:161], v[198:201], 0
	v_mfma_f32_16x16x32_bf16 v[2:5], v[166:169], v[198:201], 0
	v_mfma_f32_16x16x32_bf16 v[46:49], v[162:165], v[178:181], v[46:49]
	v_mfma_f32_16x16x32_bf16 v[14:17], v[170:173], v[178:181], v[14:17]
	v_mfma_f32_16x16x32_bf16 v[42:45], v[162:165], v[186:189], v[42:45]
	v_mfma_f32_16x16x32_bf16 v[10:13], v[170:173], v[186:189], v[10:13]
	v_mfma_f32_16x16x32_bf16 v[38:41], v[162:165], v[194:197], v[38:41]
	v_mfma_f32_16x16x32_bf16 v[6:9], v[170:173], v[194:197], v[6:9]
	v_mfma_f32_16x16x32_bf16 v[34:37], v[162:165], v[202:205], v[34:37]
	v_mfma_f32_16x16x32_bf16 v[2:5], v[170:173], v[202:205], v[2:5]
	s_setprio 0
	s_barrier
	s_add_i32 s31, 0, 0x18000
	v_add_u32_e32 v149, s31, v146
	s_add_i32 s62, 0, 0x1c000
	ds_read_b128 v[130:133], v149
	ds_read_b128 v[142:145], v149 offset:1024
	ds_read_b128 v[150:153], v149 offset:2048
	ds_read_b128 v[154:157], v149 offset:3072
	v_add_u32_e32 v149, s62, v146
	ds_read_b128 v[158:161], v149
	ds_read_b128 v[162:165], v149 offset:1024
	ds_read_b128 v[166:169], v149 offset:2048
	ds_read_b128 v[170:173], v149 offset:3072
	s_add_u32 s20, s20, s4
	s_addc_u32 s21, s21, s5
	s_mov_b32 m0, s53
	v_lshl_add_u64 v[226:227], s[20:21], 0, v[136:137]
	ds_read_b128 v[174:177], v148 offset:32768
	ds_read_b128 v[178:181], v148 offset:33792
	ds_read_b128 v[182:185], v148 offset:34816
	ds_read_b128 v[186:189], v148 offset:35840
	ds_read_b128 v[190:193], v148 offset:36864
	ds_read_b128 v[194:197], v148 offset:37888
	ds_read_b128 v[198:201], v148 offset:38912
	ds_read_b128 v[202:205], v148 offset:39936
	global_load_lds_dwordx4 v[226:227], off
	v_lshl_add_u64 v[226:227], s[20:21], 0, v[134:135]
	s_mov_b32 m0, s56
	s_nop 0
	global_load_lds_dwordx4 v[226:227], off
	s_waitcnt vmcnt(8)
	s_waitcnt lgkmcnt(0)
	s_barrier
	s_setprio 1
	s_waitcnt lgkmcnt(0)
	v_mfma_f32_16x16x32_bf16 v[126:129], v[130:133], v[174:177], v[126:129]
	v_mfma_f32_16x16x32_bf16 v[94:97], v[150:153], v[174:177], v[94:97]
	v_mfma_f32_16x16x32_bf16 v[122:125], v[130:133], v[182:185], v[122:125]
	v_mfma_f32_16x16x32_bf16 v[90:93], v[150:153], v[182:185], v[90:93]
	v_mfma_f32_16x16x32_bf16 v[118:121], v[130:133], v[190:193], v[118:121]
	v_mfma_f32_16x16x32_bf16 v[86:89], v[150:153], v[190:193], v[86:89]
	v_mfma_f32_16x16x32_bf16 v[114:117], v[130:133], v[198:201], v[114:117]
	v_mfma_f32_16x16x32_bf16 v[82:85], v[150:153], v[198:201], v[82:85]
	v_mfma_f32_16x16x32_bf16 v[126:129], v[142:145], v[178:181], v[126:129]
	v_mfma_f32_16x16x32_bf16 v[94:97], v[154:157], v[178:181], v[94:97]
	v_mfma_f32_16x16x32_bf16 v[122:125], v[142:145], v[186:189], v[122:125]
	v_mfma_f32_16x16x32_bf16 v[90:93], v[154:157], v[186:189], v[90:93]
	v_mfma_f32_16x16x32_bf16 v[118:121], v[142:145], v[194:197], v[118:121]
	v_mfma_f32_16x16x32_bf16 v[86:89], v[154:157], v[194:197], v[86:89]
	v_mfma_f32_16x16x32_bf16 v[114:117], v[142:145], v[202:205], v[114:117]
	v_mfma_f32_16x16x32_bf16 v[82:85], v[154:157], v[202:205], v[82:85]
	s_setprio 0
	s_setprio 1
	v_mfma_f32_16x16x32_bf16 v[62:65], v[158:161], v[174:177], v[62:65]
	v_mfma_f32_16x16x32_bf16 v[30:33], v[166:169], v[174:177], v[30:33]
	v_mfma_f32_16x16x32_bf16 v[58:61], v[158:161], v[182:185], v[58:61]
	v_mfma_f32_16x16x32_bf16 v[26:29], v[166:169], v[182:185], v[26:29]
	v_mfma_f32_16x16x32_bf16 v[54:57], v[158:161], v[190:193], v[54:57]
	v_mfma_f32_16x16x32_bf16 v[22:25], v[166:169], v[190:193], v[22:25]
	v_mfma_f32_16x16x32_bf16 v[50:53], v[158:161], v[198:201], v[50:53]
	v_mfma_f32_16x16x32_bf16 v[18:21], v[166:169], v[198:201], v[18:21]
	v_mfma_f32_16x16x32_bf16 v[62:65], v[162:165], v[178:181], v[62:65]
	v_mfma_f32_16x16x32_bf16 v[30:33], v[170:173], v[178:181], v[30:33]
	v_mfma_f32_16x16x32_bf16 v[58:61], v[162:165], v[186:189], v[58:61]
	v_mfma_f32_16x16x32_bf16 v[26:29], v[170:173], v[186:189], v[26:29]
	v_mfma_f32_16x16x32_bf16 v[54:57], v[162:165], v[194:197], v[54:57]
	v_mfma_f32_16x16x32_bf16 v[22:25], v[170:173], v[194:197], v[22:25]
	v_mfma_f32_16x16x32_bf16 v[50:53], v[162:165], v[202:205], v[50:53]
	v_mfma_f32_16x16x32_bf16 v[18:21], v[170:173], v[202:205], v[18:21]
	s_setprio 0
	s_barrier
	s_add_i32 s20, s31, s22
	v_lshl_add_u64 v[214:215], v[214:215], 0, s[60:61]
	s_mov_b32 m0, s20
	ds_read_b128 v[174:177], v148 offset:49152
	ds_read_b128 v[178:181], v148 offset:50176
	ds_read_b128 v[182:185], v148 offset:51200
	ds_read_b128 v[186:189], v148 offset:52224
	ds_read_b128 v[190:193], v148 offset:53248
	ds_read_b128 v[194:197], v148 offset:54272
	ds_read_b128 v[198:201], v148 offset:55296
	ds_read_b128 v[202:205], v148 offset:56320
	global_load_lds_dwordx4 v[214:215], off
	v_lshl_add_u64 v[214:215], v[216:217], 0, s[60:61]
	s_add_i32 m0, s20, 0x2000
	s_add_i32 s20, s62, s22
	global_load_lds_dwordx4 v[214:215], off
	v_lshl_add_u64 v[214:215], v[218:219], 0, s[60:61]
	s_mov_b32 m0, s20
	s_nop 0
	global_load_lds_dwordx4 v[214:215], off
	v_lshl_add_u64 v[214:215], v[220:221], 0, s[60:61]
	s_add_i32 m0, s20, 0x2000
	s_nop 0
	global_load_lds_dwordx4 v[214:215], off
	v_lshl_add_u64 v[214:215], v[222:223], 0, s[60:61]
	s_mov_b32 m0, s57
	s_nop 0
	global_load_lds_dwordx4 v[214:215], off
	v_lshl_add_u64 v[214:215], v[224:225], 0, s[60:61]
	s_mov_b32 m0, s65
	s_nop 0
	global_load_lds_dwordx4 v[214:215], off
	s_waitcnt vmcnt(8)
	s_waitcnt lgkmcnt(0)
	s_barrier
	s_setprio 1
	s_waitcnt lgkmcnt(0)
	v_mfma_f32_16x16x32_bf16 v[110:113], v[130:133], v[174:177], v[110:113]
	v_mfma_f32_16x16x32_bf16 v[78:81], v[150:153], v[174:177], v[78:81]
	v_mfma_f32_16x16x32_bf16 v[106:109], v[130:133], v[182:185], v[106:109]
	v_mfma_f32_16x16x32_bf16 v[74:77], v[150:153], v[182:185], v[74:77]
	v_mfma_f32_16x16x32_bf16 v[102:105], v[130:133], v[190:193], v[102:105]
	v_mfma_f32_16x16x32_bf16 v[70:73], v[150:153], v[190:193], v[70:73]
	v_mfma_f32_16x16x32_bf16 v[98:101], v[130:133], v[198:201], v[98:101]
	v_mfma_f32_16x16x32_bf16 v[66:69], v[150:153], v[198:201], v[66:69]
	v_mfma_f32_16x16x32_bf16 v[110:113], v[142:145], v[178:181], v[110:113]
	v_mfma_f32_16x16x32_bf16 v[78:81], v[154:157], v[178:181], v[78:81]
	v_mfma_f32_16x16x32_bf16 v[106:109], v[142:145], v[186:189], v[106:109]
	v_mfma_f32_16x16x32_bf16 v[74:77], v[154:157], v[186:189], v[74:77]
	v_mfma_f32_16x16x32_bf16 v[102:105], v[142:145], v[194:197], v[102:105]
	v_mfma_f32_16x16x32_bf16 v[70:73], v[154:157], v[194:197], v[70:73]
	v_mfma_f32_16x16x32_bf16 v[98:101], v[142:145], v[202:205], v[98:101]
	v_mfma_f32_16x16x32_bf16 v[66:69], v[154:157], v[202:205], v[66:69]
	s_setprio 0
	s_setprio 1
	v_mfma_f32_16x16x32_bf16 v[46:49], v[158:161], v[174:177], v[46:49]
	v_mfma_f32_16x16x32_bf16 v[14:17], v[166:169], v[174:177], v[14:17]
	v_mfma_f32_16x16x32_bf16 v[42:45], v[158:161], v[182:185], v[42:45]
	v_mfma_f32_16x16x32_bf16 v[10:13], v[166:169], v[182:185], v[10:13]
	v_mfma_f32_16x16x32_bf16 v[38:41], v[158:161], v[190:193], v[38:41]
	v_mfma_f32_16x16x32_bf16 v[6:9], v[166:169], v[190:193], v[6:9]
	v_mfma_f32_16x16x32_bf16 v[34:37], v[158:161], v[198:201], v[34:37]
	v_mfma_f32_16x16x32_bf16 v[2:5], v[166:169], v[198:201], v[2:5]
	v_mfma_f32_16x16x32_bf16 v[46:49], v[162:165], v[178:181], v[46:49]
	v_mfma_f32_16x16x32_bf16 v[14:17], v[170:173], v[178:181], v[14:17]
	v_mfma_f32_16x16x32_bf16 v[42:45], v[162:165], v[186:189], v[42:45]
	v_mfma_f32_16x16x32_bf16 v[10:13], v[170:173], v[186:189], v[10:13]
	v_mfma_f32_16x16x32_bf16 v[38:41], v[162:165], v[194:197], v[38:41]
	v_mfma_f32_16x16x32_bf16 v[6:9], v[170:173], v[194:197], v[6:9]
	v_mfma_f32_16x16x32_bf16 v[34:37], v[162:165], v[202:205], v[34:37]
	v_mfma_f32_16x16x32_bf16 v[2:5], v[170:173], v[202:205], v[2:5]
	s_setprio 0
	s_barrier
	s_add_u32 s18, s18, 0x100
	s_addc_u32 s19, s19, 0
	s_add_u32 s71, s71, 0x100
	s_addc_u32 s72, s72, 0
	s_cmp_ge_i32 s73, s66
	s_mov_b32 s20, s73
	s_cbranch_scc1 .LBB0_1013
	.p2alignl 6, 3212836864

.LBB0_1141:
	s_add_u32 s0, s6, 0x80
	s_addc_u32 s1, s7, 0
	s_add_u32 s6, s4, 0x100
	s_addc_u32 s7, s5, 0
	s_mov_b32 s4, 0
	s_add_i32 s9, s4, 2
	s_add_u32 s10, s0, 0x80
	s_addc_u32 s5, s1, 0
	s_add_i32 s31, 0, 0x10000
	s_cmp_eq_u32 s77, s4
	s_cselect_b32 s5, s23, s5
	s_cselect_b32 s4, s22, s10
	v_add_u32_e32 v1, s31, v165
	s_cselect_b32 s11, s67, s7
	s_cselect_b32 s10, s66, s6
	s_add_i32 s53, 0, 0x14000
	ds_read_b128 v[82:85], v1
	ds_read_b128 v[86:89], v1 offset:1024
	ds_read_b128 v[138:141], v1 offset:2048
	ds_read_b128 v[142:145], v1 offset:3072
	v_add_u32_e32 v1, s53, v165
	ds_read_b128 v[158:161], v1
	ds_read_b128 v[168:171], v1 offset:1024
	ds_read_b128 v[172:175], v1 offset:2048
	ds_read_b128 v[176:179], v1 offset:3072
	v_lshl_add_u64 v[162:163], s[0:1], 0, v[154:155]
	s_add_i32 m0, s70, 0xc000
	ds_read_b128 v[180:183], v167
	ds_read_b128 v[184:187], v167 offset:1024
	ds_read_b128 v[188:191], v167 offset:2048
	ds_read_b128 v[192:195], v167 offset:3072
	ds_read_b128 v[196:199], v167 offset:4096
	ds_read_b128 v[200:203], v167 offset:5120
	ds_read_b128 v[214:217], v167 offset:6144
	ds_read_b128 v[218:221], v167 offset:7168
	global_load_lds_dwordx4 v[162:163], off
	v_lshl_add_u64 v[162:163], s[0:1], 0, v[156:157]
	s_add_i32 m0, s70, 0xe000
	s_nop 0
	global_load_lds_dwordx4 v[162:163], off
	s_waitcnt vmcnt(8)
	s_waitcnt lgkmcnt(0)
	s_barrier
	s_setprio 1
	s_waitcnt lgkmcnt(0)
	v_mfma_f32_16x16x32_bf16 v[134:137], v[82:85], v[180:183], 0
	v_mfma_f32_16x16x32_bf16 v[130:133], v[138:141], v[180:183], 0
	v_mfma_f32_16x16x32_bf16 v[126:129], v[82:85], v[188:191], 0
	v_mfma_f32_16x16x32_bf16 v[122:125], v[138:141], v[188:191], 0
	v_mfma_f32_16x16x32_bf16 v[118:121], v[82:85], v[196:199], 0
	v_mfma_f32_16x16x32_bf16 v[114:117], v[138:141], v[196:199], 0
	v_mfma_f32_16x16x32_bf16 v[110:113], v[82:85], v[214:217], 0
	v_mfma_f32_16x16x32_bf16 v[106:109], v[138:141], v[214:217], 0
	v_mfma_f32_16x16x32_bf16 v[134:137], v[86:89], v[184:187], v[134:137]
	v_mfma_f32_16x16x32_bf16 v[130:133], v[142:145], v[184:187], v[130:133]
	v_mfma_f32_16x16x32_bf16 v[126:129], v[86:89], v[192:195], v[126:129]
	v_mfma_f32_16x16x32_bf16 v[122:125], v[142:145], v[192:195], v[122:125]
	v_mfma_f32_16x16x32_bf16 v[118:121], v[86:89], v[200:203], v[118:121]
	v_mfma_f32_16x16x32_bf16 v[114:117], v[142:145], v[200:203], v[114:117]
	v_mfma_f32_16x16x32_bf16 v[110:113], v[86:89], v[218:221], v[110:113]
	v_mfma_f32_16x16x32_bf16 v[106:109], v[142:145], v[218:221], v[106:109]
	s_setprio 0
	s_setprio 1
	v_mfma_f32_16x16x32_bf16 v[62:65], v[158:161], v[180:183], 0
	v_mfma_f32_16x16x32_bf16 v[58:61], v[172:175], v[180:183], 0
	v_mfma_f32_16x16x32_bf16 v[54:57], v[158:161], v[188:191], 0
	v_mfma_f32_16x16x32_bf16 v[50:53], v[172:175], v[188:191], 0
	v_mfma_f32_16x16x32_bf16 v[46:49], v[158:161], v[196:199], 0
	v_mfma_f32_16x16x32_bf16 v[42:45], v[172:175], v[196:199], 0
	v_mfma_f32_16x16x32_bf16 v[38:41], v[158:161], v[214:217], 0
	v_mfma_f32_16x16x32_bf16 v[34:37], v[172:175], v[214:217], 0
	v_mfma_f32_16x16x32_bf16 v[62:65], v[168:171], v[184:187], v[62:65]
	v_mfma_f32_16x16x32_bf16 v[58:61], v[176:179], v[184:187], v[58:61]
	v_mfma_f32_16x16x32_bf16 v[54:57], v[168:171], v[192:195], v[54:57]
	v_mfma_f32_16x16x32_bf16 v[50:53], v[176:179], v[192:195], v[50:53]
	v_mfma_f32_16x16x32_bf16 v[46:49], v[168:171], v[200:203], v[46:49]
	v_mfma_f32_16x16x32_bf16 v[42:45], v[176:179], v[200:203], v[42:45]
	v_mfma_f32_16x16x32_bf16 v[38:41], v[168:171], v[218:221], v[38:41]
	v_mfma_f32_16x16x32_bf16 v[34:37], v[176:179], v[218:221], v[34:37]
	s_setprio 0
	s_barrier
	s_add_i32 s31, s31, s65
	v_lshl_add_u64 v[162:163], s[10:11], 0, v[150:151]
	s_mov_b32 m0, s31
	ds_read_b128 v[180:183], v167 offset:16384
	ds_read_b128 v[184:187], v167 offset:17408
	ds_read_b128 v[188:191], v167 offset:18432
	ds_read_b128 v[192:195], v167 offset:19456
	ds_read_b128 v[196:199], v167 offset:20480
	ds_read_b128 v[200:203], v167 offset:21504
	ds_read_b128 v[214:217], v167 offset:22528
	ds_read_b128 v[218:221], v167 offset:23552
	global_load_lds_dwordx4 v[162:163], off
	s_add_i32 m0, s31, 0x2000
	v_lshl_add_u64 v[204:205], s[10:11], 0, v[146:147]
	s_add_u32 s10, s10, s12
	s_addc_u32 s11, s11, s13
	s_add_i32 s31, s53, s65
	global_load_lds_dwordx4 v[204:205], off
	v_lshl_add_u64 v[222:223], s[10:11], 0, v[150:151]
	s_mov_b32 m0, s31
	v_lshl_add_u64 v[224:225], s[10:11], 0, v[146:147]
	global_load_lds_dwordx4 v[222:223], off
	s_add_i32 m0, s31, 0x2000
	v_lshl_add_u64 v[226:227], s[4:5], 0, v[152:153]
	global_load_lds_dwordx4 v[224:225], off
	s_mov_b32 m0, s70
	v_lshl_add_u64 v[236:237], s[4:5], 0, v[148:149]
	global_load_lds_dwordx4 v[226:227], off
	s_mov_b32 m0, s71
	s_nop 0
	global_load_lds_dwordx4 v[236:237], off
	s_waitcnt vmcnt(8)
	s_waitcnt lgkmcnt(0)
	s_barrier
	s_setprio 1
	s_waitcnt lgkmcnt(0)
	v_mfma_f32_16x16x32_bf16 v[102:105], v[82:85], v[180:183], 0
	v_mfma_f32_16x16x32_bf16 v[98:101], v[138:141], v[180:183], 0
	v_mfma_f32_16x16x32_bf16 v[94:97], v[82:85], v[188:191], 0
	v_mfma_f32_16x16x32_bf16 v[90:93], v[138:141], v[188:191], 0
	v_mfma_f32_16x16x32_bf16 v[78:81], v[82:85], v[196:199], 0
	v_mfma_f32_16x16x32_bf16 v[74:77], v[138:141], v[196:199], 0
	v_mfma_f32_16x16x32_bf16 v[70:73], v[82:85], v[214:217], 0
	v_mfma_f32_16x16x32_bf16 v[66:69], v[138:141], v[214:217], 0
	v_mfma_f32_16x16x32_bf16 v[102:105], v[86:89], v[184:187], v[102:105]
	v_mfma_f32_16x16x32_bf16 v[98:101], v[142:145], v[184:187], v[98:101]
	v_mfma_f32_16x16x32_bf16 v[94:97], v[86:89], v[192:195], v[94:97]
	v_mfma_f32_16x16x32_bf16 v[90:93], v[142:145], v[192:195], v[90:93]
	v_mfma_f32_16x16x32_bf16 v[78:81], v[86:89], v[200:203], v[78:81]
	v_mfma_f32_16x16x32_bf16 v[74:77], v[142:145], v[200:203], v[74:77]
	v_mfma_f32_16x16x32_bf16 v[70:73], v[86:89], v[218:221], v[70:73]
	v_mfma_f32_16x16x32_bf16 v[66:69], v[142:145], v[218:221], v[66:69]
	s_setprio 0
	s_setprio 1
	v_mfma_f32_16x16x32_bf16 v[30:33], v[158:161], v[180:183], 0
	v_mfma_f32_16x16x32_bf16 v[26:29], v[172:175], v[180:183], 0
	v_mfma_f32_16x16x32_bf16 v[22:25], v[158:161], v[188:191], 0
	v_mfma_f32_16x16x32_bf16 v[18:21], v[172:175], v[188:191], 0
	v_mfma_f32_16x16x32_bf16 v[14:17], v[158:161], v[196:199], 0
	v_mfma_f32_16x16x32_bf16 v[10:13], v[172:175], v[196:199], 0
	v_mfma_f32_16x16x32_bf16 v[6:9], v[158:161], v[214:217], 0
	v_mfma_f32_16x16x32_bf16 v[2:5], v[172:175], v[214:217], 0
	v_mfma_f32_16x16x32_bf16 v[30:33], v[168:171], v[184:187], v[30:33]
	v_mfma_f32_16x16x32_bf16 v[26:29], v[176:179], v[184:187], v[26:29]
	v_mfma_f32_16x16x32_bf16 v[22:25], v[168:171], v[192:195], v[22:25]
	v_mfma_f32_16x16x32_bf16 v[18:21], v[176:179], v[192:195], v[18:21]
	v_mfma_f32_16x16x32_bf16 v[14:17], v[168:171], v[200:203], v[14:17]
	v_mfma_f32_16x16x32_bf16 v[10:13], v[176:179], v[200:203], v[10:13]
	v_mfma_f32_16x16x32_bf16 v[6:9], v[168:171], v[218:221], v[6:9]
	v_mfma_f32_16x16x32_bf16 v[2:5], v[176:179], v[218:221], v[2:5]
	s_setprio 0
	s_barrier
	s_add_i32 s10, 0, 0x18000
	v_add_u32_e32 v1, s10, v165
	s_add_i32 s11, 0, 0x1c000
	ds_read_b128 v[82:85], v1
	ds_read_b128 v[86:89], v1 offset:1024
	ds_read_b128 v[138:141], v1 offset:2048
	ds_read_b128 v[142:145], v1 offset:3072
	v_add_u32_e32 v1, s11, v165
	ds_read_b128 v[158:161], v1
	ds_read_b128 v[168:171], v1 offset:1024
	ds_read_b128 v[172:175], v1 offset:2048
	ds_read_b128 v[176:179], v1 offset:3072
	s_add_u32 s4, s4, s12
	s_addc_u32 s5, s5, s13
	s_mov_b32 m0, s72
	v_lshl_add_u64 v[238:239], s[4:5], 0, v[152:153]
	ds_read_b128 v[180:183], v167 offset:32768
	ds_read_b128 v[184:187], v167 offset:33792
	ds_read_b128 v[188:191], v167 offset:34816
	ds_read_b128 v[192:195], v167 offset:35840
	ds_read_b128 v[196:199], v167 offset:36864
	ds_read_b128 v[200:203], v167 offset:37888
	ds_read_b128 v[214:217], v167 offset:38912
	ds_read_b128 v[218:221], v167 offset:39936
	global_load_lds_dwordx4 v[238:239], off
	v_lshl_add_u64 v[238:239], s[4:5], 0, v[148:149]
	s_mov_b32 m0, s73
	s_nop 0
	global_load_lds_dwordx4 v[238:239], off
	s_waitcnt vmcnt(8)
	s_waitcnt lgkmcnt(0)
	s_barrier
	s_setprio 1
	s_waitcnt lgkmcnt(0)
	v_mfma_f32_16x16x32_bf16 v[134:137], v[82:85], v[180:183], v[134:137]
	v_mfma_f32_16x16x32_bf16 v[130:133], v[138:141], v[180:183], v[130:133]
	v_mfma_f32_16x16x32_bf16 v[126:129], v[82:85], v[188:191], v[126:129]
	v_mfma_f32_16x16x32_bf16 v[122:125], v[138:141], v[188:191], v[122:125]
	v_mfma_f32_16x16x32_bf16 v[118:121], v[82:85], v[196:199], v[118:121]
	v_mfma_f32_16x16x32_bf16 v[114:117], v[138:141], v[196:199], v[114:117]
	v_mfma_f32_16x16x32_bf16 v[110:113], v[82:85], v[214:217], v[110:113]
	v_mfma_f32_16x16x32_bf16 v[106:109], v[138:141], v[214:217], v[106:109]
	v_mfma_f32_16x16x32_bf16 v[134:137], v[86:89], v[184:187], v[134:137]
	v_mfma_f32_16x16x32_bf16 v[130:133], v[142:145], v[184:187], v[130:133]
	v_mfma_f32_16x16x32_bf16 v[126:129], v[86:89], v[192:195], v[126:129]
	v_mfma_f32_16x16x32_bf16 v[122:125], v[142:145], v[192:195], v[122:125]
	v_mfma_f32_16x16x32_bf16 v[118:121], v[86:89], v[200:203], v[118:121]
	v_mfma_f32_16x16x32_bf16 v[114:117], v[142:145], v[200:203], v[114:117]
	v_mfma_f32_16x16x32_bf16 v[110:113], v[86:89], v[218:221], v[110:113]
	v_mfma_f32_16x16x32_bf16 v[106:109], v[142:145], v[218:221], v[106:109]
	s_setprio 0
	s_setprio 1
	v_mfma_f32_16x16x32_bf16 v[62:65], v[158:161], v[180:183], v[62:65]
	v_mfma_f32_16x16x32_bf16 v[58:61], v[172:175], v[180:183], v[58:61]
	v_mfma_f32_16x16x32_bf16 v[54:57], v[158:161], v[188:191], v[54:57]
	v_mfma_f32_16x16x32_bf16 v[50:53], v[172:175], v[188:191], v[50:53]
	v_mfma_f32_16x16x32_bf16 v[46:49], v[158:161], v[196:199], v[46:49]
	v_mfma_f32_16x16x32_bf16 v[42:45], v[172:175], v[196:199], v[42:45]
	v_mfma_f32_16x16x32_bf16 v[38:41], v[158:161], v[214:217], v[38:41]
	v_mfma_f32_16x16x32_bf16 v[34:37], v[172:175], v[214:217], v[34:37]
	v_mfma_f32_16x16x32_bf16 v[62:65], v[168:171], v[184:187], v[62:65]
	v_mfma_f32_16x16x32_bf16 v[58:61], v[176:179], v[184:187], v[58:61]
	v_mfma_f32_16x16x32_bf16 v[54:57], v[168:171], v[192:195], v[54:57]
	v_mfma_f32_16x16x32_bf16 v[50:53], v[176:179], v[192:195], v[50:53]
	v_mfma_f32_16x16x32_bf16 v[46:49], v[168:171], v[200:203], v[46:49]
	v_mfma_f32_16x16x32_bf16 v[42:45], v[176:179], v[200:203], v[42:45]
	v_mfma_f32_16x16x32_bf16 v[38:41], v[168:171], v[218:221], v[38:41]
	v_mfma_f32_16x16x32_bf16 v[34:37], v[176:179], v[218:221], v[34:37]
	s_setprio 0
	s_barrier
	s_add_i32 s4, s10, s65
	v_lshl_add_u64 v[162:163], v[162:163], 0, s[60:61]
	s_mov_b32 m0, s4
	ds_read_b128 v[180:183], v167 offset:49152
	ds_read_b128 v[184:187], v167 offset:50176
	ds_read_b128 v[188:191], v167 offset:51200
	ds_read_b128 v[192:195], v167 offset:52224
	ds_read_b128 v[196:199], v167 offset:53248
	ds_read_b128 v[200:203], v167 offset:54272
	ds_read_b128 v[214:217], v167 offset:55296
	ds_read_b128 v[218:221], v167 offset:56320
	global_load_lds_dwordx4 v[162:163], off
	v_lshl_add_u64 v[162:163], v[204:205], 0, s[60:61]
	s_add_i32 m0, s4, 0x2000
	s_add_i32 s4, s11, s65
	global_load_lds_dwordx4 v[162:163], off
	v_lshl_add_u64 v[162:163], v[222:223], 0, s[60:61]
	s_mov_b32 m0, s4
	s_nop 0
	global_load_lds_dwordx4 v[162:163], off
	v_lshl_add_u64 v[162:163], v[224:225], 0, s[60:61]
	s_add_i32 m0, s4, 0x2000
	s_nop 0
	global_load_lds_dwordx4 v[162:163], off
	v_lshl_add_u64 v[162:163], v[226:227], 0, s[60:61]
	s_mov_b32 m0, s74
	s_nop 0
	global_load_lds_dwordx4 v[162:163], off
	v_lshl_add_u64 v[162:163], v[236:237], 0, s[60:61]
	s_mov_b32 m0, s75
	s_nop 0
	global_load_lds_dwordx4 v[162:163], off
	s_waitcnt vmcnt(8)
	s_waitcnt lgkmcnt(0)
	s_barrier
	s_setprio 1
	s_waitcnt lgkmcnt(0)
	v_mfma_f32_16x16x32_bf16 v[102:105], v[82:85], v[180:183], v[102:105]
	v_mfma_f32_16x16x32_bf16 v[98:101], v[138:141], v[180:183], v[98:101]
	v_mfma_f32_16x16x32_bf16 v[94:97], v[82:85], v[188:191], v[94:97]
	v_mfma_f32_16x16x32_bf16 v[90:93], v[138:141], v[188:191], v[90:93]
	v_mfma_f32_16x16x32_bf16 v[78:81], v[82:85], v[196:199], v[78:81]
	v_mfma_f32_16x16x32_bf16 v[74:77], v[138:141], v[196:199], v[74:77]
	v_mfma_f32_16x16x32_bf16 v[70:73], v[82:85], v[214:217], v[70:73]
	v_mfma_f32_16x16x32_bf16 v[66:69], v[138:141], v[214:217], v[66:69]
	v_mfma_f32_16x16x32_bf16 v[102:105], v[86:89], v[184:187], v[102:105]
	v_mfma_f32_16x16x32_bf16 v[98:101], v[142:145], v[184:187], v[98:101]
	v_mfma_f32_16x16x32_bf16 v[94:97], v[86:89], v[192:195], v[94:97]
	v_mfma_f32_16x16x32_bf16 v[90:93], v[142:145], v[192:195], v[90:93]
	v_mfma_f32_16x16x32_bf16 v[78:81], v[86:89], v[200:203], v[78:81]
	v_mfma_f32_16x16x32_bf16 v[74:77], v[142:145], v[200:203], v[74:77]
	v_mfma_f32_16x16x32_bf16 v[70:73], v[86:89], v[218:221], v[70:73]
	v_mfma_f32_16x16x32_bf16 v[66:69], v[142:145], v[218:221], v[66:69]
	s_setprio 0
	s_setprio 1
	v_mfma_f32_16x16x32_bf16 v[30:33], v[158:161], v[180:183], v[30:33]
	v_mfma_f32_16x16x32_bf16 v[26:29], v[172:175], v[180:183], v[26:29]
	v_mfma_f32_16x16x32_bf16 v[22:25], v[158:161], v[188:191], v[22:25]
	v_mfma_f32_16x16x32_bf16 v[18:21], v[172:175], v[188:191], v[18:21]
	v_mfma_f32_16x16x32_bf16 v[14:17], v[158:161], v[196:199], v[14:17]
	v_mfma_f32_16x16x32_bf16 v[10:13], v[172:175], v[196:199], v[10:13]
	v_mfma_f32_16x16x32_bf16 v[6:9], v[158:161], v[214:217], v[6:9]
	v_mfma_f32_16x16x32_bf16 v[2:5], v[172:175], v[214:217], v[2:5]
	v_mfma_f32_16x16x32_bf16 v[30:33], v[168:171], v[184:187], v[30:33]
	v_mfma_f32_16x16x32_bf16 v[26:29], v[176:179], v[184:187], v[26:29]
	v_mfma_f32_16x16x32_bf16 v[22:25], v[168:171], v[192:195], v[22:25]
	v_mfma_f32_16x16x32_bf16 v[18:21], v[176:179], v[192:195], v[18:21]
	v_mfma_f32_16x16x32_bf16 v[14:17], v[168:171], v[200:203], v[14:17]
	v_mfma_f32_16x16x32_bf16 v[10:13], v[176:179], v[200:203], v[10:13]
	v_mfma_f32_16x16x32_bf16 v[6:9], v[168:171], v[218:221], v[6:9]
	v_mfma_f32_16x16x32_bf16 v[2:5], v[176:179], v[218:221], v[2:5]
	s_setprio 0
	s_barrier
	s_add_u32 s0, s0, 0x100
	s_addc_u32 s1, s1, 0
	s_add_u32 s6, s6, 0x100
	s_addc_u32 s7, s7, 0
	s_cmp_ge_i32 s9, s76
	s_mov_b32 s4, s9
	s_cbranch_scc1 .Lin1_exit
	.p2alignl 6, 3212836864
